# SwiGLU epilogue element math re-emitted with folded scale factors in batches of 4; dead residual-split code removed from the residual epilogues
# speedup vs baseline: 1.0560x; 1.0023x over previous
.LBB0_414:
	v_lshl_add_u32 v166, s55, 8, v170
	v_lshl_or_b32 v158, s54, 8, v197
	v_ashrrev_i32_e32 v167, 31, v166
	v_lshlrev_b64 v[120:121], 11, v[166:167]
	v_ashrrev_i32_e32 v159, 31, v158
	v_lshl_add_u64 v[160:161], s[42:43], 0, v[120:121]
	v_lshlrev_b64 v[120:121], 1, v[158:159]
	v_lshl_add_u64 v[194:195], v[160:161], 0, v[120:121]
	global_load_dwordx4 v[200:203], v[194:195], off
	global_load_dwordx4 v[144:147], v[194:195], off offset:256
	v_or_b32_e32 v190, 16, v166
	v_ashrrev_i32_e32 v191, 31, v190
	v_lshlrev_b64 v[122:123], 11, v[190:191]
	v_or_b32_e32 v162, 32, v166
	v_lshl_add_u64 v[122:123], s[42:43], 0, v[122:123]
	v_ashrrev_i32_e32 v163, 31, v162
	v_lshl_add_u64 v[192:193], v[122:123], 0, v[120:121]
	v_lshlrev_b64 v[122:123], 11, v[162:163]
	v_lshl_add_u64 v[122:123], s[42:43], 0, v[122:123]
	v_lshl_add_u64 v[164:165], v[122:123], 0, v[120:121]
	global_load_dwordx4 v[136:139], v[192:193], off
	global_load_dwordx4 v[128:131], v[192:193], off offset:256
	global_load_dwordx4 v[124:127], v[164:165], off
	global_load_dwordx4 v[120:123], v[164:165], off offset:256
	s_lshl_b32 s16, s54, 2
	s_ashr_i32 s17, s16, 31
	s_waitcnt vmcnt(0)
	v_lshlrev_b32_e32 v178, 16, v200
	v_and_b32_e32 v179, 0xffff0000, v200
	v_add_f32_e32 v178, 0, v178
	v_add_f32_e32 v179, 0, v179
	v_add_f32_e32 v140, v140, v178
	v_add_f32_e32 v141, v141, v179
	v_lshlrev_b32_e32 v178, 16, v201
	v_and_b32_e32 v179, 0xffff0000, v201
	v_add_f32_e32 v178, 0, v178
	v_add_f32_e32 v179, 0, v179
	v_add_f32_e32 v142, v142, v178
	v_add_f32_e32 v143, v143, v179
	v_lshlrev_b32_e32 v178, 16, v202
	v_and_b32_e32 v179, 0xffff0000, v202
	v_add_f32_e32 v178, 0, v178
	v_add_f32_e32 v179, 0, v179
	v_add_f32_e32 v178, v132, v178
	v_add_f32_e32 v179, v133, v179
	v_lshlrev_b32_e32 v132, 16, v203
	v_and_b32_e32 v133, 0xffff0000, v203
	v_add_f32_e32 v132, 0, v132
	v_add_f32_e32 v133, 0, v133
	v_add_f32_e32 v180, v134, v132
	v_add_f32_e32 v181, v135, v133
	v_cvt_pk_bf16_f32 v132, v140, v141
	s_nop 0
	v_mul_f32_e32 v134, v141, v141
	v_cvt_pk_bf16_f32 v133, v142, v143
	v_fmac_f32_e32 v134, v140, v140
	s_nop 0
	v_mul_f32_e32 v135, v143, v143
	v_fmac_f32_e32 v135, v142, v142
	v_add_f32_e32 v135, v134, v135
	v_cvt_pk_bf16_f32 v134, v178, v179
	s_nop 0
	s_nop 0
	v_mul_f32_e32 v140, v179, v179
	v_fmac_f32_e32 v140, v178, v178
	v_add_f32_e32 v140, v140, v135
	v_cvt_pk_bf16_f32 v135, v180, v181
	s_nop 0
	global_store_dwordx4 v[194:195], v[132:135], off
	v_mul_f32_e32 v141, v181, v181
	v_fmac_f32_e32 v141, v180, v180
	v_lshlrev_b32_e32 v132, 16, v144
	v_and_b32_e32 v133, 0xffff0000, v144
	v_add_f32_e32 v132, 0, v132
	v_add_f32_e32 v133, 0, v133
	v_add_f32_e32 v116, v116, v132
	v_add_f32_e32 v117, v117, v133
	v_lshlrev_b32_e32 v132, 16, v145
	v_and_b32_e32 v133, 0xffff0000, v145
	v_add_f32_e32 v132, 0, v132
	v_add_f32_e32 v133, 0, v133
	v_add_f32_e32 v118, v118, v132
	v_add_f32_e32 v119, v119, v133
	v_lshlrev_b32_e32 v132, 16, v146
	v_and_b32_e32 v133, 0xffff0000, v146
	v_add_f32_e32 v132, 0, v132
	v_add_f32_e32 v133, 0, v133
	v_add_f32_e32 v132, v112, v132
	v_add_f32_e32 v133, v113, v133
	v_lshlrev_b32_e32 v112, 16, v147
	v_and_b32_e32 v113, 0xffff0000, v147
	v_add_f32_e32 v112, 0, v112
	v_add_f32_e32 v113, 0, v113
	v_add_f32_e32 v134, v114, v112
	v_add_f32_e32 v135, v115, v113
	v_cvt_pk_bf16_f32 v112, v116, v117
	v_add_f32_e32 v140, v141, v140
	s_nop 0
	v_mul_f32_e32 v113, v117, v117
	v_fmac_f32_e32 v113, v116, v116
	v_add_f32_e32 v114, v113, v140
	v_cvt_pk_bf16_f32 v113, v118, v119
	s_nop 0
	s_nop 0
	v_mul_f32_e32 v115, v119, v119
	v_fmac_f32_e32 v115, v118, v118
	v_add_f32_e32 v115, v115, v114
	v_cvt_pk_bf16_f32 v114, v132, v133
	s_nop 0
	s_nop 0
	v_mul_f32_e32 v116, v133, v133
	v_fmac_f32_e32 v116, v132, v132
	v_add_f32_e32 v116, v116, v115
	v_cvt_pk_bf16_f32 v115, v134, v135
	s_nop 0
	global_store_dwordx4 v[194:195], v[112:115], off offset:256
	v_mul_f32_e32 v117, v135, v135
	v_fmac_f32_e32 v117, v134, v134
	v_and_b32_e32 v113, 64, v213
	v_xor_b32_e32 v112, 16, v213
	v_add_u32_e32 v113, 64, v113
	v_cmp_lt_i32_e32 vcc, v112, v113
	v_add_f32_e32 v116, v117, v116
	v_xor_b32_e32 v114, 32, v213
	v_cndmask_b32_e32 v112, v213, v112, vcc
	v_lshlrev_b32_e32 v140, 2, v112
	ds_bpermute_b32 v112, v140, v116
	v_cmp_lt_i32_e32 vcc, v114, v113
	s_waitcnt lgkmcnt(0)
	v_add_f32_e32 v112, v116, v112
	v_cndmask_b32_e32 v113, v213, v114, vcc
	v_lshlrev_b32_e32 v141, 2, v113
	ds_bpermute_b32 v113, v141, v112
	s_and_saveexec_b64 s[18:19], s[2:3]
	s_mov_b64 s[56:57], s[44:45]
	s_cbranch_execz .LBB0_416
	s_waitcnt lgkmcnt(0)
	v_add_f32_e32 v114, v112, v113
	v_lshlrev_b64 v[112:113], 6, v[166:167]
	v_lshl_add_u64 v[112:113], s[40:41], 0, v[112:113]
	v_lshl_add_u64 v[112:113], s[16:17], 2, v[112:113]
	s_lshl_b32 s90, s35, 2
	v_lshl_add_u64 v[112:113], v[112:113], 0, s[90:91]
	global_store_dword v[112:113], v114, off
.LBB0_416:
	s_or_b64 exec, exec, s[18:19]
	v_or_b32_e32 v132, 48, v166
	v_ashrrev_i32_e32 v133, 31, v132
	s_waitcnt lgkmcnt(0)
	v_lshlrev_b64 v[112:113], 11, v[132:133]
	v_lshl_add_u64 v[112:113], s[42:43], 0, v[112:113]
	v_lshl_add_u64 v[134:135], v[158:159], 1, v[112:113]
	global_load_dwordx4 v[116:119], v[134:135], off
	global_load_dwordx4 v[112:115], v[134:135], off offset:256
	v_lshlrev_b32_e32 v142, 16, v136
	v_and_b32_e32 v136, 0xffff0000, v136
	v_add_f32_e32 v136, 0, v136
	v_add_f32_e32 v109, v109, v136
	v_lshlrev_b32_e32 v136, 16, v137
	v_and_b32_e32 v137, 0xffff0000, v137
	v_add_f32_e32 v136, 0, v136
	v_add_f32_e32 v137, 0, v137
	v_add_f32_e32 v110, v110, v136
	v_add_f32_e32 v111, v111, v137
	v_lshlrev_b32_e32 v136, 16, v138
	v_and_b32_e32 v137, 0xffff0000, v138
	v_add_f32_e32 v136, 0, v136
	v_add_f32_e32 v137, 0, v137
	v_add_f32_e32 v136, v104, v136
	v_add_f32_e32 v137, v105, v137
	v_lshlrev_b32_e32 v104, 16, v139
	v_and_b32_e32 v105, 0xffff0000, v139
	v_add_f32_e32 v142, 0, v142
	v_add_f32_e32 v104, 0, v104
	v_add_f32_e32 v105, 0, v105
	v_add_f32_e32 v108, v108, v142
	v_add_f32_e32 v138, v106, v104
	v_add_f32_e32 v139, v107, v105
	v_cvt_pk_bf16_f32 v104, v108, v109
	s_nop 0
	v_mul_f32_e32 v106, v109, v109
	v_cvt_pk_bf16_f32 v105, v110, v111
	v_fmac_f32_e32 v106, v108, v108
	s_nop 0
	v_mul_f32_e32 v107, v111, v111
	v_fmac_f32_e32 v107, v110, v110
	v_add_f32_e32 v107, v106, v107
	v_cvt_pk_bf16_f32 v106, v136, v137
	s_nop 0
	s_nop 0
	v_mul_f32_e32 v108, v137, v137
	v_fmac_f32_e32 v108, v136, v136
	v_add_f32_e32 v108, v108, v107
	v_cvt_pk_bf16_f32 v107, v138, v139
	s_nop 0
	global_store_dwordx4 v[192:193], v[104:107], off
	v_mul_f32_e32 v109, v139, v139
	v_fmac_f32_e32 v109, v138, v138
	v_lshlrev_b32_e32 v104, 16, v128
	v_and_b32_e32 v105, 0xffff0000, v128
	v_add_f32_e32 v104, 0, v104
	v_add_f32_e32 v105, 0, v105
	v_add_f32_e32 v100, v100, v104
	v_add_f32_e32 v101, v101, v105
	v_lshlrev_b32_e32 v104, 16, v129
	v_and_b32_e32 v105, 0xffff0000, v129
	v_add_f32_e32 v104, 0, v104
	v_add_f32_e32 v105, 0, v105
	v_add_f32_e32 v102, v102, v104
	v_add_f32_e32 v103, v103, v105
	v_lshlrev_b32_e32 v104, 16, v130
	v_and_b32_e32 v105, 0xffff0000, v130
	v_add_f32_e32 v104, 0, v104
	v_add_f32_e32 v105, 0, v105
	v_add_f32_e32 v96, v96, v104
	v_add_f32_e32 v97, v97, v105
	v_lshlrev_b32_e32 v104, 16, v131
	v_and_b32_e32 v105, 0xffff0000, v131
	v_add_f32_e32 v104, 0, v104
	v_add_f32_e32 v105, 0, v105
	v_add_f32_e32 v104, v98, v104
	v_add_f32_e32 v105, v99, v105
	v_cvt_pk_bf16_f32 v98, v100, v101
	v_add_f32_e32 v108, v109, v108
	s_nop 0
	v_mul_f32_e32 v99, v101, v101
	v_fmac_f32_e32 v99, v100, v100
	v_add_f32_e32 v100, v99, v108
	v_cvt_pk_bf16_f32 v99, v102, v103
	s_nop 0
	s_nop 0
	v_mul_f32_e32 v101, v103, v103
	v_fmac_f32_e32 v101, v102, v102
	v_add_f32_e32 v101, v101, v100
	v_cvt_pk_bf16_f32 v100, v96, v97
	s_nop 0
	v_mul_f32_e32 v97, v97, v97
	v_fmac_f32_e32 v97, v96, v96
	v_add_f32_e32 v96, v97, v101
	v_mul_f32_e32 v97, v105, v105
	v_fmac_f32_e32 v97, v104, v104
	v_add_f32_e32 v96, v97, v96
	ds_bpermute_b32 v97, v140, v96
	s_waitcnt lgkmcnt(0)
	v_add_f32_e32 v96, v96, v97
	ds_bpermute_b32 v97, v141, v96
	v_cvt_pk_bf16_f32 v101, v104, v105
	s_nop 0
	global_store_dwordx4 v[192:193], v[98:101], off offset:256
	s_and_saveexec_b64 s[18:19], s[2:3]
	s_cbranch_execz .LBB0_418
	s_waitcnt lgkmcnt(0)
	v_add_f32_e32 v98, v96, v97
	v_lshlrev_b64 v[96:97], 6, v[190:191]
	v_lshl_add_u64 v[96:97], s[40:41], 0, v[96:97]
	v_lshl_add_u64 v[96:97], s[16:17], 2, v[96:97]
	s_lshl_b32 s90, s35, 2
	v_lshl_add_u64 v[96:97], v[96:97], 0, s[90:91]
	global_store_dword v[96:97], v98, off
.LBB0_418:
	s_or_b64 exec, exec, s[18:19]
	v_add_u32_e32 v104, 0x80, v166
	v_ashrrev_i32_e32 v105, 31, v104
	s_waitcnt lgkmcnt(0)
	v_lshlrev_b64 v[96:97], 11, v[104:105]
	v_lshl_add_u64 v[96:97], s[42:43], 0, v[96:97]
	v_lshl_add_u64 v[106:107], v[158:159], 1, v[96:97]
	global_load_dwordx4 v[100:103], v[106:107], off
	global_load_dwordx4 v[96:99], v[106:107], off offset:256
	v_lshlrev_b32_e32 v108, 16, v124
	v_and_b32_e32 v109, 0xffff0000, v124
	v_add_f32_e32 v108, 0, v108
	v_add_f32_e32 v109, 0, v109
	v_add_f32_e32 v92, v92, v108
	v_add_f32_e32 v93, v93, v109
	v_lshlrev_b32_e32 v108, 16, v125
	v_and_b32_e32 v109, 0xffff0000, v125
	v_add_f32_e32 v108, 0, v108
	v_add_f32_e32 v109, 0, v109
	v_add_f32_e32 v94, v94, v108
	v_add_f32_e32 v95, v95, v109
	v_lshlrev_b32_e32 v108, 16, v126
	v_and_b32_e32 v109, 0xffff0000, v126
	v_add_f32_e32 v108, 0, v108
	v_add_f32_e32 v109, 0, v109
	v_add_f32_e32 v108, v88, v108
	v_add_f32_e32 v109, v89, v109
	v_lshlrev_b32_e32 v88, 16, v127
	v_and_b32_e32 v89, 0xffff0000, v127
	v_add_f32_e32 v88, 0, v88
	v_add_f32_e32 v89, 0, v89
	v_add_f32_e32 v110, v90, v88
	v_add_f32_e32 v111, v91, v89
	v_cvt_pk_bf16_f32 v88, v92, v93
	s_nop 0
	v_mul_f32_e32 v90, v93, v93
	v_cvt_pk_bf16_f32 v89, v94, v95
	v_fmac_f32_e32 v90, v92, v92
	s_nop 0
	v_mul_f32_e32 v91, v95, v95
	v_fmac_f32_e32 v91, v94, v94
	v_add_f32_e32 v91, v90, v91
	v_cvt_pk_bf16_f32 v90, v108, v109
	s_nop 0
	s_nop 0
	v_mul_f32_e32 v92, v109, v109
	v_fmac_f32_e32 v92, v108, v108
	v_add_f32_e32 v92, v92, v91
	v_cvt_pk_bf16_f32 v91, v110, v111
	s_nop 0
	v_and_b32_e32 v94, 0xffff0000, v91
	v_sub_f32_e32 v94, v111, v94
	global_store_dwordx4 v[164:165], v[88:91], off
	v_mul_f32_e32 v93, v111, v111
	v_fmac_f32_e32 v93, v110, v110
	v_lshlrev_b32_e32 v88, 16, v120
	v_and_b32_e32 v89, 0xffff0000, v120
	v_add_f32_e32 v88, 0, v88
	v_add_f32_e32 v89, 0, v89
	v_add_f32_e32 v84, v84, v88
	v_add_f32_e32 v85, v85, v89
	v_lshlrev_b32_e32 v88, 16, v121
	v_and_b32_e32 v89, 0xffff0000, v121
	v_add_f32_e32 v88, 0, v88
	v_add_f32_e32 v89, 0, v89
	v_add_f32_e32 v86, v86, v88
	v_add_f32_e32 v87, v87, v89
	v_lshlrev_b32_e32 v88, 16, v122
	v_and_b32_e32 v89, 0xffff0000, v122
	v_add_f32_e32 v88, 0, v88
	v_add_f32_e32 v89, 0, v89
	v_add_f32_e32 v80, v80, v88
	v_add_f32_e32 v81, v81, v89
	v_lshlrev_b32_e32 v88, 16, v123
	v_and_b32_e32 v89, 0xffff0000, v123
	v_add_f32_e32 v88, 0, v88
	v_add_f32_e32 v89, 0, v89
	v_add_f32_e32 v88, v82, v88
	v_add_f32_e32 v89, v83, v89
	v_cvt_pk_bf16_f32 v82, v84, v85
	v_add_f32_e32 v92, v93, v92
	s_nop 0
	v_mul_f32_e32 v83, v85, v85
	v_fmac_f32_e32 v83, v84, v84
	v_add_f32_e32 v84, v83, v92
	v_cvt_pk_bf16_f32 v83, v86, v87
	s_nop 0
	s_nop 0
	v_mul_f32_e32 v85, v87, v87
	v_fmac_f32_e32 v85, v86, v86
	v_add_f32_e32 v85, v85, v84
	v_cvt_pk_bf16_f32 v84, v80, v81
	s_nop 0
	v_mul_f32_e32 v81, v81, v81
	v_fmac_f32_e32 v81, v80, v80
	v_add_f32_e32 v80, v81, v85
	v_mul_f32_e32 v81, v89, v89
	v_fmac_f32_e32 v81, v88, v88
	v_add_f32_e32 v80, v81, v80
	ds_bpermute_b32 v81, v140, v80
	s_waitcnt lgkmcnt(0)
	v_add_f32_e32 v80, v80, v81
	ds_bpermute_b32 v81, v141, v80
	v_cvt_pk_bf16_f32 v85, v88, v89
	s_nop 0
	global_store_dwordx4 v[164:165], v[82:85], off offset:256
	s_and_saveexec_b64 s[18:19], s[2:3]
	s_cbranch_execz .LBB0_420
	s_waitcnt lgkmcnt(0)
	v_add_f32_e32 v82, v80, v81
	v_lshlrev_b64 v[80:81], 6, v[162:163]
	v_lshl_add_u64 v[80:81], s[40:41], 0, v[80:81]
	v_lshl_add_u64 v[80:81], s[16:17], 2, v[80:81]
	s_lshl_b32 s90, s35, 2
	v_lshl_add_u64 v[80:81], v[80:81], 0, s[90:91]
	global_store_dword v[80:81], v82, off
.LBB0_420:
	s_or_b64 exec, exec, s[18:19]
	s_waitcnt lgkmcnt(0)
	v_lshl_add_u64 v[80:81], v[158:159], 1, v[160:161]
	s_mov_b64 s[18:19], 0x48000
	v_lshl_add_u64 v[88:89], v[80:81], 0, s[18:19]
	v_add_co_u32_e32 v80, vcc, 0x48000, v80
	s_waitcnt vmcnt(7)
	v_lshlrev_b32_e32 v90, 16, v116
	v_addc_co_u32_e32 v81, vcc, 0, v81, vcc
	global_load_dwordx4 v[84:87], v[80:81], off
	s_nop 0
	global_load_dwordx4 v[80:83], v[88:89], off offset:256
	v_and_b32_e32 v91, 0xffff0000, v116
	v_add_f32_e32 v90, 0, v90
	v_add_f32_e32 v91, 0, v91
	v_add_f32_e32 v76, v76, v90
	v_add_f32_e32 v77, v77, v91
	v_lshlrev_b32_e32 v90, 16, v117
	v_and_b32_e32 v91, 0xffff0000, v117
	v_add_f32_e32 v90, 0, v90
	v_add_f32_e32 v91, 0, v91
	v_add_f32_e32 v78, v78, v90
	v_add_f32_e32 v79, v79, v91
	v_lshlrev_b32_e32 v90, 16, v118
	v_and_b32_e32 v91, 0xffff0000, v118
	v_add_f32_e32 v90, 0, v90
	v_add_f32_e32 v91, 0, v91
	v_add_f32_e32 v90, v72, v90
	v_add_f32_e32 v91, v73, v91
	v_lshlrev_b32_e32 v72, 16, v119
	v_and_b32_e32 v73, 0xffff0000, v119
	v_add_f32_e32 v72, 0, v72
	v_add_f32_e32 v73, 0, v73
	v_add_f32_e32 v92, v74, v72
	v_add_f32_e32 v93, v75, v73
	v_cvt_pk_bf16_f32 v72, v76, v77
	s_nop 0
	v_mul_f32_e32 v74, v77, v77
	v_cvt_pk_bf16_f32 v73, v78, v79
	v_fmac_f32_e32 v74, v76, v76
	s_nop 0
	v_mul_f32_e32 v75, v79, v79
	v_fmac_f32_e32 v75, v78, v78
	v_add_f32_e32 v75, v74, v75
	v_cvt_pk_bf16_f32 v74, v90, v91
	s_nop 0
	s_nop 0
	v_mul_f32_e32 v76, v91, v91
	v_fmac_f32_e32 v76, v90, v90
	v_add_f32_e32 v76, v76, v75
	v_cvt_pk_bf16_f32 v75, v92, v93
	s_nop 0
	global_store_dwordx4 v[134:135], v[72:75], off
	v_mul_f32_e32 v77, v93, v93
	v_fmac_f32_e32 v77, v92, v92
	s_waitcnt vmcnt(9)
	v_lshlrev_b32_e32 v72, 16, v112
	v_and_b32_e32 v73, 0xffff0000, v112
	v_add_f32_e32 v72, 0, v72
	v_add_f32_e32 v73, 0, v73
	v_add_f32_e32 v68, v68, v72
	v_add_f32_e32 v69, v69, v73
	v_lshlrev_b32_e32 v72, 16, v113
	v_and_b32_e32 v73, 0xffff0000, v113
	v_add_f32_e32 v72, 0, v72
	v_add_f32_e32 v73, 0, v73
	v_add_f32_e32 v70, v70, v72
	v_add_f32_e32 v71, v71, v73
	v_lshlrev_b32_e32 v72, 16, v114
	v_and_b32_e32 v73, 0xffff0000, v114
	v_add_f32_e32 v72, 0, v72
	v_add_f32_e32 v73, 0, v73
	v_add_f32_e32 v64, v64, v72
	v_add_f32_e32 v65, v65, v73
	v_lshlrev_b32_e32 v72, 16, v115
	v_and_b32_e32 v73, 0xffff0000, v115
	v_add_f32_e32 v72, 0, v72
	v_add_f32_e32 v73, 0, v73
	v_add_f32_e32 v72, v66, v72
	v_add_f32_e32 v73, v67, v73
	v_cvt_pk_bf16_f32 v66, v68, v69
	v_add_f32_e32 v76, v77, v76
	s_nop 0
	v_mul_f32_e32 v67, v69, v69
	v_fmac_f32_e32 v67, v68, v68
	v_add_f32_e32 v68, v67, v76
	v_cvt_pk_bf16_f32 v67, v70, v71
	s_nop 0
	s_nop 0
	v_mul_f32_e32 v69, v71, v71
	v_fmac_f32_e32 v69, v70, v70
	v_add_f32_e32 v69, v69, v68
	v_cvt_pk_bf16_f32 v68, v64, v65
	s_nop 0
	v_mul_f32_e32 v65, v65, v65
	v_fmac_f32_e32 v65, v64, v64
	v_add_f32_e32 v64, v65, v69
	v_mul_f32_e32 v65, v73, v73
	v_fmac_f32_e32 v65, v72, v72
	v_add_f32_e32 v64, v65, v64
	ds_bpermute_b32 v65, v140, v64
	s_waitcnt lgkmcnt(0)
	v_add_f32_e32 v64, v64, v65
	ds_bpermute_b32 v65, v141, v64
	v_cvt_pk_bf16_f32 v69, v72, v73
	s_nop 0
	global_store_dwordx4 v[134:135], v[66:69], off offset:256
	s_and_saveexec_b64 s[18:19], s[2:3]
	s_cbranch_execz .LBB0_422
	s_waitcnt lgkmcnt(0)
	v_add_f32_e32 v66, v64, v65
	v_lshlrev_b64 v[64:65], 6, v[132:133]
	v_lshl_add_u64 v[64:65], s[40:41], 0, v[64:65]
	v_lshl_add_u64 v[64:65], s[16:17], 2, v[64:65]
	s_lshl_b32 s90, s35, 2
	v_lshl_add_u64 v[64:65], v[64:65], 0, s[90:91]
	global_store_dword v[64:65], v66, off
.LBB0_422:
	s_or_b64 exec, exec, s[18:19]
	v_or_b32_e32 v72, 32, v104
	v_ashrrev_i32_e32 v73, 31, v72
	s_waitcnt lgkmcnt(0)
	v_lshlrev_b64 v[64:65], 11, v[72:73]
	v_lshl_add_u64 v[64:65], s[42:43], 0, v[64:65]
	v_lshl_add_u64 v[74:75], v[158:159], 1, v[64:65]
	global_load_dwordx4 v[68:71], v[74:75], off
	global_load_dwordx4 v[64:67], v[74:75], off offset:256
	s_waitcnt vmcnt(9)
	v_lshlrev_b32_e32 v76, 16, v100
	v_and_b32_e32 v77, 0xffff0000, v100
	v_add_f32_e32 v76, 0, v76
	v_add_f32_e32 v77, 0, v77
	v_add_f32_e32 v60, v60, v76
	v_add_f32_e32 v61, v61, v77
	v_lshlrev_b32_e32 v76, 16, v101
	v_and_b32_e32 v77, 0xffff0000, v101
	v_add_f32_e32 v76, 0, v76
	v_add_f32_e32 v77, 0, v77
	v_add_f32_e32 v62, v62, v76
	v_add_f32_e32 v63, v63, v77
	v_lshlrev_b32_e32 v76, 16, v102
	v_and_b32_e32 v77, 0xffff0000, v102
	v_add_f32_e32 v76, 0, v76
	v_add_f32_e32 v77, 0, v77
	v_add_f32_e32 v76, v56, v76
	v_add_f32_e32 v77, v57, v77
	v_lshlrev_b32_e32 v56, 16, v103
	v_and_b32_e32 v57, 0xffff0000, v103
	v_add_f32_e32 v56, 0, v56
	v_add_f32_e32 v57, 0, v57
	v_add_f32_e32 v78, v58, v56
	v_add_f32_e32 v79, v59, v57
	v_cvt_pk_bf16_f32 v56, v60, v61
	s_nop 0
	v_mul_f32_e32 v58, v61, v61
	v_cvt_pk_bf16_f32 v57, v62, v63
	v_fmac_f32_e32 v58, v60, v60
	s_nop 0
	v_mul_f32_e32 v59, v63, v63
	v_fmac_f32_e32 v59, v62, v62
	v_add_f32_e32 v59, v58, v59
	v_cvt_pk_bf16_f32 v58, v76, v77
	s_nop 0
	s_nop 0
	v_mul_f32_e32 v60, v77, v77
	v_fmac_f32_e32 v60, v76, v76
	v_add_f32_e32 v60, v60, v59
	v_cvt_pk_bf16_f32 v59, v78, v79
	s_nop 0
	global_store_dwordx4 v[106:107], v[56:59], off
	v_mul_f32_e32 v61, v79, v79
	v_fmac_f32_e32 v61, v78, v78
	s_waitcnt vmcnt(9)
	v_lshlrev_b32_e32 v56, 16, v96
	v_and_b32_e32 v57, 0xffff0000, v96
	v_add_f32_e32 v56, 0, v56
	v_add_f32_e32 v57, 0, v57
	v_add_f32_e32 v52, v52, v56
	v_add_f32_e32 v53, v53, v57
	v_lshlrev_b32_e32 v56, 16, v97
	v_and_b32_e32 v57, 0xffff0000, v97
	v_add_f32_e32 v56, 0, v56
	v_add_f32_e32 v57, 0, v57
	v_add_f32_e32 v54, v54, v56
	v_add_f32_e32 v55, v55, v57
	v_lshlrev_b32_e32 v56, 16, v98
	v_and_b32_e32 v57, 0xffff0000, v98
	v_add_f32_e32 v56, 0, v56
	v_add_f32_e32 v57, 0, v57
	v_add_f32_e32 v48, v48, v56
	v_add_f32_e32 v49, v49, v57
	v_lshlrev_b32_e32 v56, 16, v99
	v_and_b32_e32 v57, 0xffff0000, v99
	v_add_f32_e32 v56, 0, v56
	v_add_f32_e32 v57, 0, v57
	v_add_f32_e32 v56, v50, v56
	v_add_f32_e32 v57, v51, v57
	v_cvt_pk_bf16_f32 v50, v52, v53
	v_add_f32_e32 v60, v61, v60
	s_nop 0
	v_mul_f32_e32 v51, v53, v53
	v_fmac_f32_e32 v51, v52, v52
	v_add_f32_e32 v52, v51, v60
	v_cvt_pk_bf16_f32 v51, v54, v55
	s_nop 0
	s_nop 0
	v_mul_f32_e32 v53, v55, v55
	v_fmac_f32_e32 v53, v54, v54
	v_add_f32_e32 v53, v53, v52
	v_cvt_pk_bf16_f32 v52, v48, v49
	s_nop 0
	v_mul_f32_e32 v49, v49, v49
	v_fmac_f32_e32 v49, v48, v48
	v_add_f32_e32 v48, v49, v53
	v_mul_f32_e32 v49, v57, v57
	v_fmac_f32_e32 v49, v56, v56
	v_add_f32_e32 v48, v49, v48
	ds_bpermute_b32 v49, v140, v48
	s_waitcnt lgkmcnt(0)
	v_add_f32_e32 v48, v48, v49
	ds_bpermute_b32 v49, v141, v48
	v_cvt_pk_bf16_f32 v53, v56, v57
	s_nop 0
	global_store_dwordx4 v[106:107], v[50:53], off offset:256
	s_and_saveexec_b64 s[18:19], s[2:3]
	s_cbranch_execz .LBB0_424
	s_waitcnt lgkmcnt(0)
	v_add_f32_e32 v50, v48, v49
	v_lshlrev_b64 v[48:49], 6, v[104:105]
	v_lshl_add_u64 v[48:49], s[40:41], 0, v[48:49]
	v_lshl_add_u64 v[48:49], s[16:17], 2, v[48:49]
	s_lshl_b32 s90, s35, 2
	v_lshl_add_u64 v[48:49], v[48:49], 0, s[90:91]
	global_store_dword v[48:49], v50, off
.LBB0_424:
	s_or_b64 exec, exec, s[18:19]
	v_or_b32_e32 v56, 48, v104
	v_ashrrev_i32_e32 v57, 31, v56
	s_waitcnt lgkmcnt(0)
	v_lshlrev_b64 v[48:49], 11, v[56:57]
	v_lshl_add_u64 v[48:49], s[42:43], 0, v[48:49]
	v_lshl_add_u64 v[58:59], v[158:159], 1, v[48:49]
	global_load_dwordx4 v[52:55], v[58:59], off
	global_load_dwordx4 v[48:51], v[58:59], off offset:256
	s_waitcnt vmcnt(9)
	v_lshlrev_b32_e32 v60, 16, v84
	v_and_b32_e32 v61, 0xffff0000, v84
	v_add_f32_e32 v60, 0, v60
	v_add_f32_e32 v61, 0, v61
	v_add_f32_e32 v44, v44, v60
	v_add_f32_e32 v45, v45, v61
	v_lshlrev_b32_e32 v60, 16, v85
	v_and_b32_e32 v61, 0xffff0000, v85
	v_add_f32_e32 v60, 0, v60
	v_add_f32_e32 v61, 0, v61
	v_add_f32_e32 v46, v46, v60
	v_add_f32_e32 v47, v47, v61
	v_lshlrev_b32_e32 v60, 16, v86
	v_and_b32_e32 v61, 0xffff0000, v86
	v_add_f32_e32 v60, 0, v60
	v_add_f32_e32 v61, 0, v61
	v_add_f32_e32 v60, v40, v60
	v_add_f32_e32 v61, v41, v61
	v_lshlrev_b32_e32 v40, 16, v87
	v_and_b32_e32 v41, 0xffff0000, v87
	v_add_f32_e32 v40, 0, v40
	v_add_f32_e32 v41, 0, v41
	v_add_f32_e32 v62, v42, v40
	v_add_f32_e32 v63, v43, v41
	v_cvt_pk_bf16_f32 v40, v44, v45
	s_nop 0
	v_mul_f32_e32 v42, v45, v45
	v_cvt_pk_bf16_f32 v41, v46, v47
	v_fmac_f32_e32 v42, v44, v44
	s_nop 0
	v_mul_f32_e32 v43, v47, v47
	v_fmac_f32_e32 v43, v46, v46
	v_add_f32_e32 v43, v42, v43
	v_cvt_pk_bf16_f32 v42, v60, v61
	s_nop 0
	s_nop 0
	v_mul_f32_e32 v44, v61, v61
	v_fmac_f32_e32 v44, v60, v60
	v_add_f32_e32 v44, v44, v43
	v_cvt_pk_bf16_f32 v43, v62, v63
	s_nop 0
	v_and_b32_e32 v46, 0xffff0000, v43
	v_sub_f32_e32 v46, v63, v46
	global_store_dwordx4 v[88:89], v[40:43], off
	v_mul_f32_e32 v45, v63, v63
	v_fmac_f32_e32 v45, v62, v62
	s_waitcnt vmcnt(9)
	v_lshlrev_b32_e32 v40, 16, v80
	v_and_b32_e32 v41, 0xffff0000, v80
	v_add_f32_e32 v40, 0, v40
	v_add_f32_e32 v41, 0, v41
	v_add_f32_e32 v36, v36, v40
	v_add_f32_e32 v37, v37, v41
	v_lshlrev_b32_e32 v40, 16, v81
	v_and_b32_e32 v41, 0xffff0000, v81
	v_add_f32_e32 v40, 0, v40
	v_add_f32_e32 v41, 0, v41
	v_add_f32_e32 v38, v38, v40
	v_add_f32_e32 v39, v39, v41
	v_lshlrev_b32_e32 v40, 16, v82
	v_and_b32_e32 v41, 0xffff0000, v82
	v_add_f32_e32 v40, 0, v40
	v_add_f32_e32 v41, 0, v41
	v_add_f32_e32 v32, v32, v40
	v_add_f32_e32 v33, v33, v41
	v_lshlrev_b32_e32 v40, 16, v83
	v_and_b32_e32 v41, 0xffff0000, v83
	v_add_f32_e32 v40, 0, v40
	v_add_f32_e32 v41, 0, v41
	v_add_f32_e32 v40, v34, v40
	v_add_f32_e32 v41, v35, v41
	v_cvt_pk_bf16_f32 v34, v36, v37
	v_add_f32_e32 v44, v45, v44
	s_nop 0
	v_mul_f32_e32 v35, v37, v37
	v_fmac_f32_e32 v35, v36, v36
	v_add_f32_e32 v36, v35, v44
	v_cvt_pk_bf16_f32 v35, v38, v39
	s_nop 0
	v_and_b32_e32 v42, 0xffff0000, v35
	v_sub_f32_e32 v42, v39, v42
	s_nop 0
	v_mul_f32_e32 v37, v39, v39
	v_fmac_f32_e32 v37, v38, v38
	v_add_f32_e32 v37, v37, v36
	v_cvt_pk_bf16_f32 v36, v32, v33
	s_nop 0
	v_mul_f32_e32 v33, v33, v33
	v_fmac_f32_e32 v33, v32, v32
	v_add_f32_e32 v32, v33, v37
	v_mul_f32_e32 v33, v41, v41
	v_fmac_f32_e32 v33, v40, v40
	v_add_f32_e32 v32, v33, v32
	ds_bpermute_b32 v33, v140, v32
	s_waitcnt lgkmcnt(0)
	v_add_f32_e32 v32, v32, v33
	ds_bpermute_b32 v33, v141, v32
	v_cvt_pk_bf16_f32 v37, v40, v41
	s_nop 0
	v_lshlrev_b32_e32 v38, 16, v37
	v_sub_f32_e32 v38, v40, v38
	v_and_b32_e32 v39, 0xffff0000, v37
	v_sub_f32_e32 v39, v41, v39
	v_cvt_pk_bf16_f32 v38, v38, v39
	global_store_dwordx4 v[88:89], v[34:37], off offset:256
	s_and_saveexec_b64 s[18:19], s[2:3]
	s_cbranch_execz .LBB0_426
	v_or_b32_e32 v34, 16, v104
	v_ashrrev_i32_e32 v35, 31, v34
	s_waitcnt lgkmcnt(0)
	v_add_f32_e32 v36, v32, v33
	v_lshlrev_b64 v[32:33], 6, v[34:35]
	v_lshl_add_u64 v[32:33], s[40:41], 0, v[32:33]
	v_lshl_add_u64 v[32:33], s[16:17], 2, v[32:33]
	s_lshl_b32 s90, s35, 2
	v_lshl_add_u64 v[32:33], v[32:33], 0, s[90:91]
	global_store_dword v[32:33], v36, off
.LBB0_426:
	s_or_b64 exec, exec, s[18:19]
	s_waitcnt vmcnt(7)
	v_lshlrev_b32_e32 v32, 16, v68
	s_waitcnt lgkmcnt(0)
	v_and_b32_e32 v33, 0xffff0000, v68
	v_add_f32_e32 v32, 0, v32
	v_add_f32_e32 v33, 0, v33
	v_add_f32_e32 v28, v28, v32
	v_add_f32_e32 v29, v29, v33
	v_lshlrev_b32_e32 v32, 16, v69
	v_and_b32_e32 v33, 0xffff0000, v69
	v_add_f32_e32 v32, 0, v32
	v_add_f32_e32 v33, 0, v33
	v_add_f32_e32 v30, v30, v32
	v_add_f32_e32 v31, v31, v33
	v_lshlrev_b32_e32 v32, 16, v70
	v_and_b32_e32 v33, 0xffff0000, v70
	v_add_f32_e32 v32, 0, v32
	v_add_f32_e32 v33, 0, v33
	v_add_f32_e32 v32, v24, v32
	v_add_f32_e32 v33, v25, v33
	v_lshlrev_b32_e32 v24, 16, v71
	v_and_b32_e32 v25, 0xffff0000, v71
	v_add_f32_e32 v24, 0, v24
	v_add_f32_e32 v25, 0, v25
	v_add_f32_e32 v34, v26, v24
	v_add_f32_e32 v35, v27, v25
	v_cvt_pk_bf16_f32 v24, v28, v29
	s_nop 0
	v_mul_f32_e32 v26, v29, v29
	v_cvt_pk_bf16_f32 v25, v30, v31
	v_fmac_f32_e32 v26, v28, v28
	s_nop 0
	v_mul_f32_e32 v27, v31, v31
	v_fmac_f32_e32 v27, v30, v30
	v_add_f32_e32 v27, v26, v27
	v_cvt_pk_bf16_f32 v26, v32, v33
	s_nop 0
	s_nop 0
	v_mul_f32_e32 v28, v33, v33
	v_fmac_f32_e32 v28, v32, v32
	v_add_f32_e32 v28, v28, v27
	v_cvt_pk_bf16_f32 v27, v34, v35
	s_nop 0
	v_and_b32_e32 v30, 0xffff0000, v27
	v_sub_f32_e32 v30, v35, v30
	global_store_dwordx4 v[74:75], v[24:27], off
	v_mul_f32_e32 v29, v35, v35
	v_fmac_f32_e32 v29, v34, v34
	s_waitcnt vmcnt(7)
	v_lshlrev_b32_e32 v24, 16, v64
	v_and_b32_e32 v25, 0xffff0000, v64
	v_add_f32_e32 v24, 0, v24
	v_add_f32_e32 v25, 0, v25
	v_add_f32_e32 v20, v20, v24
	v_add_f32_e32 v21, v21, v25
	v_lshlrev_b32_e32 v24, 16, v65
	v_and_b32_e32 v25, 0xffff0000, v65
	v_add_f32_e32 v24, 0, v24
	v_add_f32_e32 v25, 0, v25
	v_add_f32_e32 v22, v22, v24
	v_add_f32_e32 v23, v23, v25
	v_lshlrev_b32_e32 v24, 16, v66
	v_and_b32_e32 v25, 0xffff0000, v66
	v_add_f32_e32 v24, 0, v24
	v_add_f32_e32 v25, 0, v25
	v_add_f32_e32 v16, v16, v24
	v_add_f32_e32 v17, v17, v25
	v_lshlrev_b32_e32 v24, 16, v67
	v_and_b32_e32 v25, 0xffff0000, v67
	v_add_f32_e32 v24, 0, v24
	v_add_f32_e32 v25, 0, v25
	v_add_f32_e32 v24, v18, v24
	v_add_f32_e32 v25, v19, v25
	v_cvt_pk_bf16_f32 v18, v20, v21
	v_add_f32_e32 v28, v29, v28
	s_nop 0
	v_mul_f32_e32 v19, v21, v21
	v_fmac_f32_e32 v19, v20, v20
	v_add_f32_e32 v20, v19, v28
	v_cvt_pk_bf16_f32 v19, v22, v23
	s_nop 0
	v_and_b32_e32 v26, 0xffff0000, v19
	v_sub_f32_e32 v26, v23, v26
	s_nop 0
	v_mul_f32_e32 v21, v23, v23
	v_fmac_f32_e32 v21, v22, v22
	v_add_f32_e32 v21, v21, v20
	v_cvt_pk_bf16_f32 v20, v16, v17
	s_nop 0
	v_mul_f32_e32 v17, v17, v17
	v_fmac_f32_e32 v17, v16, v16
	v_add_f32_e32 v16, v17, v21
	v_mul_f32_e32 v17, v25, v25
	v_fmac_f32_e32 v17, v24, v24
	v_add_f32_e32 v16, v17, v16
	ds_bpermute_b32 v17, v140, v16
	s_waitcnt lgkmcnt(0)
	v_add_f32_e32 v16, v16, v17
	ds_bpermute_b32 v17, v141, v16
	v_cvt_pk_bf16_f32 v21, v24, v25
	s_nop 0
	v_lshlrev_b32_e32 v22, 16, v21
	v_sub_f32_e32 v22, v24, v22
	v_and_b32_e32 v23, 0xffff0000, v21
	v_sub_f32_e32 v23, v25, v23
	v_cvt_pk_bf16_f32 v22, v22, v23
	global_store_dwordx4 v[74:75], v[18:21], off offset:256
	s_and_saveexec_b64 s[18:19], s[2:3]
	s_cbranch_execz .LBB0_428
	s_waitcnt lgkmcnt(0)
	v_add_f32_e32 v18, v16, v17
	v_lshlrev_b64 v[16:17], 6, v[72:73]
	v_lshl_add_u64 v[16:17], s[40:41], 0, v[16:17]
	v_lshl_add_u64 v[16:17], s[16:17], 2, v[16:17]
	s_lshl_b32 s90, s35, 2
	v_lshl_add_u64 v[16:17], v[16:17], 0, s[90:91]
	global_store_dword v[16:17], v18, off
.LBB0_428:
	s_or_b64 exec, exec, s[18:19]
	s_waitcnt vmcnt(5)
	v_lshlrev_b32_e32 v16, 16, v52
	s_waitcnt lgkmcnt(0)
	v_and_b32_e32 v17, 0xffff0000, v52
	v_add_f32_e32 v16, 0, v16
	v_add_f32_e32 v17, 0, v17
	v_add_f32_e32 v12, v12, v16
	v_add_f32_e32 v13, v13, v17
	v_lshlrev_b32_e32 v16, 16, v53
	v_and_b32_e32 v17, 0xffff0000, v53
	v_add_f32_e32 v16, 0, v16
	v_add_f32_e32 v17, 0, v17
	v_add_f32_e32 v14, v14, v16
	v_add_f32_e32 v15, v15, v17
	v_lshlrev_b32_e32 v16, 16, v54
	v_and_b32_e32 v17, 0xffff0000, v54
	v_add_f32_e32 v16, 0, v16
	v_add_f32_e32 v17, 0, v17
	v_add_f32_e32 v16, v8, v16
	v_add_f32_e32 v17, v9, v17
	v_lshlrev_b32_e32 v8, 16, v55
	v_and_b32_e32 v9, 0xffff0000, v55
	v_add_f32_e32 v8, 0, v8
	v_add_f32_e32 v9, 0, v9
	v_add_f32_e32 v18, v10, v8
	v_add_f32_e32 v19, v11, v9
	v_cvt_pk_bf16_f32 v8, v12, v13
	s_nop 0
	v_mul_f32_e32 v10, v13, v13
	v_cvt_pk_bf16_f32 v9, v14, v15
	v_fmac_f32_e32 v10, v12, v12
	s_nop 0
	v_mul_f32_e32 v11, v15, v15
	v_fmac_f32_e32 v11, v14, v14
	v_add_f32_e32 v11, v10, v11
	v_cvt_pk_bf16_f32 v10, v16, v17
	s_nop 0
	s_nop 0
	v_mul_f32_e32 v12, v17, v17
	v_fmac_f32_e32 v12, v16, v16
	v_add_f32_e32 v12, v12, v11
	v_cvt_pk_bf16_f32 v11, v18, v19
	s_nop 0
	v_and_b32_e32 v14, 0xffff0000, v11
	v_sub_f32_e32 v14, v19, v14
	global_store_dwordx4 v[58:59], v[8:11], off
	v_mul_f32_e32 v13, v19, v19
	v_fmac_f32_e32 v13, v18, v18
	s_waitcnt vmcnt(5)
	v_lshlrev_b32_e32 v8, 16, v48
	v_and_b32_e32 v9, 0xffff0000, v48
	v_add_f32_e32 v8, 0, v8
	v_add_f32_e32 v9, 0, v9
	v_add_f32_e32 v4, v4, v8
	v_add_f32_e32 v5, v5, v9
	v_lshlrev_b32_e32 v8, 16, v49
	v_and_b32_e32 v9, 0xffff0000, v49
	v_add_f32_e32 v8, 0, v8
	v_add_f32_e32 v9, 0, v9
	v_add_f32_e32 v6, v6, v8
	v_add_f32_e32 v7, v7, v9
	v_lshlrev_b32_e32 v8, 16, v50
	v_and_b32_e32 v9, 0xffff0000, v50
	v_add_f32_e32 v8, 0, v8
	v_add_f32_e32 v9, 0, v9
	v_add_f32_e32 v0, v0, v8
	v_add_f32_e32 v1, v1, v9
	v_lshlrev_b32_e32 v8, 16, v51
	v_and_b32_e32 v9, 0xffff0000, v51
	v_add_f32_e32 v8, 0, v8
	v_add_f32_e32 v9, 0, v9
	v_add_f32_e32 v8, v2, v8
	v_add_f32_e32 v9, v3, v9
	v_cvt_pk_bf16_f32 v2, v4, v5
	v_add_f32_e32 v12, v13, v12
	s_nop 0
	v_mul_f32_e32 v3, v5, v5
	v_fmac_f32_e32 v3, v4, v4
	v_add_f32_e32 v4, v3, v12
	v_cvt_pk_bf16_f32 v3, v6, v7
	s_nop 0
	v_and_b32_e32 v10, 0xffff0000, v3
	v_sub_f32_e32 v10, v7, v10
	s_nop 0
	v_mul_f32_e32 v5, v7, v7
	v_fmac_f32_e32 v5, v6, v6
	v_add_f32_e32 v5, v5, v4
	v_cvt_pk_bf16_f32 v4, v0, v1
	s_nop 0
	v_mul_f32_e32 v1, v1, v1
	v_fmac_f32_e32 v1, v0, v0
	v_add_f32_e32 v0, v1, v5
	v_mul_f32_e32 v1, v9, v9
	v_fmac_f32_e32 v1, v8, v8
	v_add_f32_e32 v0, v1, v0
	ds_bpermute_b32 v1, v140, v0
	s_waitcnt lgkmcnt(0)
	v_add_f32_e32 v0, v0, v1
	ds_bpermute_b32 v1, v141, v0
	v_cvt_pk_bf16_f32 v5, v8, v9
	s_nop 0
	v_lshlrev_b32_e32 v6, 16, v5
	v_sub_f32_e32 v6, v8, v6
	v_and_b32_e32 v7, 0xffff0000, v5
	v_sub_f32_e32 v7, v9, v7
	v_cvt_pk_bf16_f32 v6, v6, v7
	global_store_dwordx4 v[58:59], v[2:5], off offset:256
	s_and_saveexec_b64 s[18:19], s[2:3]
	s_cbranch_execz .LBB0_430
	s_waitcnt lgkmcnt(0)
	v_add_f32_e32 v2, v0, v1
	v_lshlrev_b64 v[0:1], 6, v[56:57]
	v_lshl_add_u64 v[0:1], s[40:41], 0, v[0:1]
	v_lshl_add_u64 v[0:1], s[16:17], 2, v[0:1]
	s_lshl_b32 s90, s35, 2
	v_lshl_add_u64 v[0:1], v[0:1], 0, s[90:91]
	global_store_dword v[0:1], v2, off

.LBB0_983:
	v_lshl_add_u32 v206, s56, 8, v170
	v_lshl_or_b32 v200, s55, 8, v221
	v_ashrrev_i32_e32 v207, 31, v206
	v_readlane_b32 s56, v252, 12
	v_lshlrev_b64 v[120:121], 12, v[206:207]
	v_readlane_b32 s57, v252, 13
	v_ashrrev_i32_e32 v201, 31, v200
	v_or_b32_e32 v208, 16, v206
	v_lshl_add_u64 v[202:203], s[56:57], 0, v[120:121]
	v_lshlrev_b64 v[120:121], 2, v[200:201]
	v_lshl_add_u64 v[122:123], v[202:203], 0, v[120:121]
	global_load_dwordx4 v[224:227], v[122:123], off offset:16
	global_load_dwordx4 v[228:231], v[122:123], off
	global_load_dwordx4 v[160:163], v[122:123], off offset:528
	global_load_dwordx4 v[164:167], v[122:123], off offset:512
	v_ashrrev_i32_e32 v209, 31, v208
	v_lshlrev_b64 v[122:123], 12, v[208:209]
	v_lshl_add_u64 v[122:123], s[56:57], 0, v[122:123]
	v_or_b32_e32 v204, 32, v206
	v_lshl_add_u64 v[122:123], v[122:123], 0, v[120:121]
	v_ashrrev_i32_e32 v205, 31, v204
	global_load_dwordx4 v[148:151], v[122:123], off offset:16
	global_load_dwordx4 v[156:159], v[122:123], off
	global_load_dwordx4 v[136:139], v[122:123], off offset:528
	global_load_dwordx4 v[140:143], v[122:123], off offset:512
	v_lshlrev_b64 v[122:123], 12, v[204:205]
	v_lshl_add_u64 v[122:123], s[56:57], 0, v[122:123]
	v_lshl_add_u64 v[124:125], v[122:123], 0, v[120:121]
	global_load_dwordx4 v[128:131], v[124:125], off offset:16
	global_load_dwordx4 v[132:135], v[124:125], off
	global_load_dwordx4 v[120:123], v[124:125], off offset:528
	s_nop 0
	global_load_dwordx4 v[124:127], v[124:125], off offset:512
	v_lshlrev_b64 v[178:179], 11, v[206:207]
	s_lshl_b32 s16, s55, 2
	s_ashr_i32 s17, s16, 31
	v_readlane_b32 s58, v252, 14
	v_readlane_b32 s59, v252, 15
	v_readlane_b32 s60, v252, 16
	v_readlane_b32 s61, v252, 17
	v_readlane_b32 s62, v252, 18
	v_readlane_b32 s63, v252, 19
	v_readlane_b32 s64, v252, 20
	v_readlane_b32 s65, v252, 21
	v_readlane_b32 s66, v252, 22
	v_readlane_b32 s67, v252, 23
	v_readlane_b32 s68, v252, 24
	v_readlane_b32 s69, v252, 25
	v_readlane_b32 s70, v252, 26
	v_readlane_b32 s71, v252, 27
	s_waitcnt vmcnt(0)
	v_add_f32_e32 v144, v144, v224
	v_add_f32_e32 v180, v152, v228
	v_add_f32_e32 v153, v153, v229
	v_cvt_pk_bf16_f32 v152, v180, v153
	v_add_f32_e32 v154, v154, v230
	v_add_f32_e32 v155, v155, v231
	v_mul_f32_e32 v181, v153, v153
	v_cvt_pk_bf16_f32 v153, v154, v155
	v_fmac_f32_e32 v181, v180, v180
	v_mul_f32_e32 v155, v155, v155
	v_fmac_f32_e32 v155, v154, v154
	v_add_f32_e32 v145, v145, v225
	v_add_f32_e32 v155, v181, v155
	v_cvt_pk_bf16_f32 v154, v144, v145
	v_add_f32_e32 v146, v146, v226
	v_mul_f32_e32 v145, v145, v145
	v_fmac_f32_e32 v145, v144, v144
	v_add_f32_e32 v147, v147, v227
	v_add_f32_e32 v144, v155, v145
	v_cvt_pk_bf16_f32 v155, v146, v147
	v_add_f32_e32 v116, v116, v164
	v_add_f32_e32 v117, v117, v165
	v_mul_f32_e32 v145, v147, v147
	v_fmac_f32_e32 v145, v146, v146
	v_add_f32_e32 v146, v145, v144
	v_lshl_add_u64 v[144:145], s[42:43], 0, v[178:179]
	v_lshl_add_u64 v[144:145], v[200:201], 1, v[144:145]
	global_store_dwordx4 v[144:145], v[152:155], off
	v_add_f32_e32 v147, v112, v160
	v_cvt_pk_bf16_f32 v112, v116, v117
	v_add_f32_e32 v118, v118, v166
	v_add_f32_e32 v152, v113, v161
	v_add_f32_e32 v153, v114, v162
	v_add_f32_e32 v114, v119, v167
	v_add_f32_e32 v119, v115, v163
	s_nop 0
	v_mul_f32_e32 v113, v117, v117
	v_fmac_f32_e32 v113, v116, v116
	v_add_f32_e32 v115, v113, v146
	v_cvt_pk_bf16_f32 v113, v118, v114
	s_nop 0
	v_mul_f32_e32 v114, v114, v114
	v_fmac_f32_e32 v114, v118, v118
	v_add_f32_e32 v115, v114, v115
	v_cvt_pk_bf16_f32 v114, v147, v152
	s_nop 0
	s_nop 0
	v_mul_f32_e32 v116, v152, v152
	v_fmac_f32_e32 v116, v147, v147
	v_add_f32_e32 v116, v116, v115
	v_cvt_pk_bf16_f32 v115, v153, v119
	s_nop 0
	global_store_dwordx4 v[144:145], v[112:115], off offset:256
	v_mul_f32_e32 v117, v119, v119
	v_fmac_f32_e32 v117, v153, v153
	v_and_b32_e32 v113, 64, v213
	v_xor_b32_e32 v112, 16, v213
	v_add_u32_e32 v113, 64, v113
	v_cmp_lt_i32_e32 vcc, v112, v113
	v_add_f32_e32 v116, v117, v116
	v_xor_b32_e32 v114, 32, v213
	v_cndmask_b32_e32 v112, v213, v112, vcc
	v_lshlrev_b32_e32 v162, 2, v112
	ds_bpermute_b32 v112, v162, v116
	v_cmp_lt_i32_e32 vcc, v114, v113
	s_waitcnt lgkmcnt(0)
	v_add_f32_e32 v112, v116, v112
	v_cndmask_b32_e32 v113, v213, v114, vcc
	v_lshlrev_b32_e32 v163, 2, v113
	ds_bpermute_b32 v113, v163, v112
	s_and_saveexec_b64 s[18:19], s[2:3]
	s_cbranch_execz .LBB0_985
	v_lshlrev_b64 v[114:115], 6, v[206:207]
	v_lshl_add_u64 v[114:115], s[40:41], 0, v[114:115]
	v_lshl_add_u64 v[114:115], s[16:17], 2, v[114:115]
	s_lshl_b32 s90, s35, 2
	v_lshl_add_u64 v[114:115], v[114:115], 0, s[90:91]
	s_waitcnt lgkmcnt(0)
	v_add_f32_e32 v112, v112, v113
	global_store_dword v[114:115], v112, off
.LBB0_985:
	s_or_b64 exec, exec, s[18:19]
	v_or_b32_e32 v160, 48, v206
	v_ashrrev_i32_e32 v161, 31, v160
	v_readlane_b32 s56, v252, 12
	s_waitcnt lgkmcnt(0)
	v_lshlrev_b64 v[112:113], 12, v[160:161]
	v_readlane_b32 s57, v252, 13
	v_add_f32_e32 v108, v108, v156
	v_add_f32_e32 v148, v104, v148
	v_lshl_add_u64 v[112:113], s[56:57], 0, v[112:113]
	v_lshl_add_u64 v[116:117], v[200:201], 2, v[112:113]
	global_load_dwordx4 v[144:147], v[116:117], off offset:16
	global_load_dwordx4 v[152:155], v[116:117], off
	global_load_dwordx4 v[112:115], v[116:117], off offset:528
	s_nop 0
	global_load_dwordx4 v[116:119], v[116:117], off offset:512
	v_add_f32_e32 v109, v109, v157
	v_add_f32_e32 v149, v105, v149
	v_add_f32_e32 v150, v106, v150
	v_add_f32_e32 v106, v111, v159
	v_add_f32_e32 v111, v107, v151
	v_cvt_pk_bf16_f32 v104, v108, v109
	v_add_f32_e32 v110, v110, v158
	v_mul_f32_e32 v107, v109, v109
	v_fmac_f32_e32 v107, v108, v108
	v_cvt_pk_bf16_f32 v105, v110, v106
	v_lshlrev_b64 v[164:165], 11, v[208:209]
	v_mul_f32_e32 v106, v106, v106
	v_fmac_f32_e32 v106, v110, v110
	v_add_f32_e32 v107, v107, v106
	v_cvt_pk_bf16_f32 v106, v148, v149
	v_add_f32_e32 v100, v100, v140
	v_add_f32_e32 v101, v101, v141
	v_mul_f32_e32 v108, v149, v149
	v_fmac_f32_e32 v108, v148, v148
	v_add_f32_e32 v108, v107, v108
	v_cvt_pk_bf16_f32 v107, v150, v111
	v_add_f32_e32 v102, v102, v142
	v_add_f32_e32 v103, v103, v143
	v_mul_f32_e32 v109, v111, v111
	v_fmac_f32_e32 v109, v150, v150
	v_add_f32_e32 v110, v109, v108
	v_lshl_add_u64 v[108:109], s[42:43], 0, v[164:165]
	v_lshl_add_u64 v[108:109], v[200:201], 1, v[108:109]
	global_store_dwordx4 v[108:109], v[104:107], off
	v_add_f32_e32 v96, v96, v136
	v_add_f32_e32 v97, v97, v137
	v_add_f32_e32 v104, v98, v138
	v_add_f32_e32 v105, v99, v139
	v_cvt_pk_bf16_f32 v98, v100, v101
	v_readlane_b32 s58, v252, 14
	v_readlane_b32 s59, v252, 15
	v_mul_f32_e32 v99, v101, v101
	v_fmac_f32_e32 v99, v100, v100
	v_add_f32_e32 v100, v99, v110
	v_cvt_pk_bf16_f32 v99, v102, v103
	v_readlane_b32 s60, v252, 16
	v_readlane_b32 s61, v252, 17
	v_mul_f32_e32 v101, v103, v103
	v_fmac_f32_e32 v101, v102, v102
	v_add_f32_e32 v101, v101, v100
	v_cvt_pk_bf16_f32 v100, v96, v97
	v_readlane_b32 s62, v252, 18
	v_mul_f32_e32 v97, v97, v97
	v_fmac_f32_e32 v97, v96, v96
	v_add_f32_e32 v96, v97, v101
	v_mul_f32_e32 v97, v105, v105
	v_fmac_f32_e32 v97, v104, v104
	v_add_f32_e32 v96, v97, v96
	ds_bpermute_b32 v97, v162, v96
	v_readlane_b32 s63, v252, 19
	v_cvt_pk_bf16_f32 v101, v104, v105
	v_readlane_b32 s64, v252, 20
	s_waitcnt lgkmcnt(0)
	v_add_f32_e32 v96, v96, v97
	ds_bpermute_b32 v97, v163, v96
	v_readlane_b32 s65, v252, 21
	v_readlane_b32 s66, v252, 22
	v_readlane_b32 s67, v252, 23
	v_readlane_b32 s68, v252, 24
	v_readlane_b32 s69, v252, 25
	v_readlane_b32 s70, v252, 26
	v_readlane_b32 s71, v252, 27
	global_store_dwordx4 v[108:109], v[98:101], off offset:256
	s_and_saveexec_b64 s[18:19], s[2:3]
	s_cbranch_execz .LBB0_987
	v_lshlrev_b64 v[98:99], 6, v[208:209]
	v_lshl_add_u64 v[98:99], s[40:41], 0, v[98:99]
	v_lshl_add_u64 v[98:99], s[16:17], 2, v[98:99]
	s_lshl_b32 s90, s35, 2
	v_lshl_add_u64 v[98:99], v[98:99], 0, s[90:91]
	s_waitcnt lgkmcnt(0)
	v_add_f32_e32 v96, v96, v97
	global_store_dword v[98:99], v96, off
.LBB0_987:
	s_or_b64 exec, exec, s[18:19]
	v_add_u32_e32 v136, 0x80, v206
	v_ashrrev_i32_e32 v137, 31, v136
	v_readlane_b32 s56, v252, 12
	s_waitcnt lgkmcnt(0)
	v_lshlrev_b64 v[96:97], 12, v[136:137]
	v_readlane_b32 s57, v252, 13
	v_add_f32_e32 v92, v92, v132
	v_add_f32_e32 v128, v88, v128
	v_lshl_add_u64 v[96:97], s[56:57], 0, v[96:97]
	v_lshl_add_u64 v[100:101], v[200:201], 2, v[96:97]
	global_load_dwordx4 v[104:107], v[100:101], off offset:16
	global_load_dwordx4 v[108:111], v[100:101], off
	global_load_dwordx4 v[96:99], v[100:101], off offset:528
	s_nop 0
	global_load_dwordx4 v[100:103], v[100:101], off offset:512
	v_add_f32_e32 v93, v93, v133
	v_add_f32_e32 v129, v89, v129
	v_add_f32_e32 v130, v90, v130
	v_add_f32_e32 v90, v95, v135
	v_add_f32_e32 v95, v91, v131
	v_cvt_pk_bf16_f32 v88, v92, v93
	v_add_f32_e32 v94, v94, v134
	v_mul_f32_e32 v91, v93, v93
	v_fmac_f32_e32 v91, v92, v92
	v_cvt_pk_bf16_f32 v89, v94, v90
	v_lshlrev_b64 v[138:139], 11, v[204:205]
	v_mul_f32_e32 v90, v90, v90
	v_fmac_f32_e32 v90, v94, v94
	v_add_f32_e32 v91, v91, v90
	v_cvt_pk_bf16_f32 v90, v128, v129
	v_add_f32_e32 v84, v84, v124
	v_add_f32_e32 v85, v85, v125
	v_mul_f32_e32 v92, v129, v129
	v_fmac_f32_e32 v92, v128, v128
	v_add_f32_e32 v92, v91, v92
	v_cvt_pk_bf16_f32 v91, v130, v95
	v_add_f32_e32 v86, v86, v126
	v_add_f32_e32 v87, v87, v127
	v_mul_f32_e32 v93, v95, v95
	v_fmac_f32_e32 v93, v130, v130
	v_add_f32_e32 v94, v93, v92
	v_lshl_add_u64 v[92:93], s[42:43], 0, v[138:139]
	v_lshl_add_u64 v[92:93], v[200:201], 1, v[92:93]
	global_store_dwordx4 v[92:93], v[88:91], off
	v_add_f32_e32 v80, v80, v120
	v_add_f32_e32 v81, v81, v121
	v_add_f32_e32 v88, v82, v122
	v_add_f32_e32 v89, v83, v123
	v_cvt_pk_bf16_f32 v82, v84, v85
	v_readlane_b32 s58, v252, 14
	v_readlane_b32 s59, v252, 15
	v_mul_f32_e32 v83, v85, v85
	v_fmac_f32_e32 v83, v84, v84
	v_add_f32_e32 v84, v83, v94
	v_cvt_pk_bf16_f32 v83, v86, v87
	v_readlane_b32 s60, v252, 16
	v_readlane_b32 s61, v252, 17
	v_mul_f32_e32 v85, v87, v87
	v_fmac_f32_e32 v85, v86, v86
	v_add_f32_e32 v85, v85, v84
	v_cvt_pk_bf16_f32 v84, v80, v81
	v_readlane_b32 s62, v252, 18
	v_mul_f32_e32 v81, v81, v81
	v_fmac_f32_e32 v81, v80, v80
	v_add_f32_e32 v80, v81, v85
	v_mul_f32_e32 v81, v89, v89
	v_fmac_f32_e32 v81, v88, v88
	v_add_f32_e32 v80, v81, v80
	ds_bpermute_b32 v81, v162, v80
	v_readlane_b32 s63, v252, 19
	v_cvt_pk_bf16_f32 v85, v88, v89
	v_readlane_b32 s64, v252, 20
	s_waitcnt lgkmcnt(0)
	v_add_f32_e32 v80, v80, v81
	ds_bpermute_b32 v81, v163, v80
	v_readlane_b32 s65, v252, 21
	v_readlane_b32 s66, v252, 22
	v_readlane_b32 s67, v252, 23
	v_readlane_b32 s68, v252, 24
	v_readlane_b32 s69, v252, 25
	v_readlane_b32 s70, v252, 26
	v_readlane_b32 s71, v252, 27
	global_store_dwordx4 v[92:93], v[82:85], off offset:256
	s_and_saveexec_b64 s[18:19], s[2:3]
	s_cbranch_execz .LBB0_989
	v_lshlrev_b64 v[82:83], 6, v[204:205]
	v_lshl_add_u64 v[82:83], s[40:41], 0, v[82:83]
	v_lshl_add_u64 v[82:83], s[16:17], 2, v[82:83]
	s_lshl_b32 s90, s35, 2
	v_lshl_add_u64 v[82:83], v[82:83], 0, s[90:91]
	s_waitcnt lgkmcnt(0)
	v_add_f32_e32 v80, v80, v81
	global_store_dword v[82:83], v80, off
.LBB0_989:
	s_or_b64 exec, exec, s[18:19]
	s_waitcnt lgkmcnt(0)
	v_lshl_add_u64 v[80:81], v[200:201], 2, v[202:203]
	s_mov_b64 s[18:19], 0x90000
	s_mov_b32 s9, 0x90000
	v_lshl_add_u64 v[84:85], v[80:81], 0, s[18:19]
	v_add_co_u32_e32 v80, vcc, s9, v80
	s_waitcnt vmcnt(10)
	v_add_f32_e32 v76, v76, v152
	v_addc_co_u32_e32 v81, vcc, 0, v81, vcc
	global_load_dwordx4 v[88:91], v[80:81], off
	s_nop 0
	global_load_dwordx4 v[80:83], v[84:85], off offset:528
	global_load_dwordx4 v[92:95], v[84:85], off offset:16
	s_nop 0
	global_load_dwordx4 v[84:87], v[84:85], off offset:512
	v_add_f32_e32 v122, v72, v144
	v_add_f32_e32 v77, v77, v153
	v_add_f32_e32 v123, v73, v145
	v_add_f32_e32 v124, v74, v146
	v_add_f32_e32 v74, v79, v155
	v_add_f32_e32 v79, v75, v147
	v_cvt_pk_bf16_f32 v72, v76, v77
	v_add_f32_e32 v78, v78, v154
	v_mul_f32_e32 v75, v77, v77
	v_fmac_f32_e32 v75, v76, v76
	v_cvt_pk_bf16_f32 v73, v78, v74
	v_lshlrev_b64 v[120:121], 11, v[160:161]
	v_mul_f32_e32 v74, v74, v74
	v_fmac_f32_e32 v74, v78, v78
	v_add_f32_e32 v75, v75, v74
	v_cvt_pk_bf16_f32 v74, v122, v123
	s_waitcnt vmcnt(12)
	v_add_f32_e32 v68, v68, v116
	v_add_f32_e32 v69, v69, v117
	v_mul_f32_e32 v76, v123, v123
	v_fmac_f32_e32 v76, v122, v122
	v_add_f32_e32 v76, v75, v76
	v_cvt_pk_bf16_f32 v75, v124, v79
	v_add_f32_e32 v70, v70, v118
	v_add_f32_e32 v71, v71, v119
	v_mul_f32_e32 v77, v79, v79
	v_fmac_f32_e32 v77, v124, v124
	v_add_f32_e32 v78, v77, v76
	v_lshl_add_u64 v[76:77], s[42:43], 0, v[120:121]
	v_lshl_add_u64 v[76:77], v[200:201], 1, v[76:77]
	global_store_dwordx4 v[76:77], v[72:75], off
	v_add_f32_e32 v64, v64, v112
	v_add_f32_e32 v65, v65, v113
	v_add_f32_e32 v72, v66, v114
	v_add_f32_e32 v73, v67, v115
	v_cvt_pk_bf16_f32 v66, v68, v69
	s_nop 0
	s_nop 0
	v_mul_f32_e32 v67, v69, v69
	v_fmac_f32_e32 v67, v68, v68
	v_add_f32_e32 v68, v67, v78
	v_cvt_pk_bf16_f32 v67, v70, v71
	s_nop 0
	s_nop 0
	v_mul_f32_e32 v69, v71, v71
	v_fmac_f32_e32 v69, v70, v70
	v_add_f32_e32 v69, v69, v68
	v_cvt_pk_bf16_f32 v68, v64, v65
	s_nop 0
	v_mul_f32_e32 v65, v65, v65
	v_fmac_f32_e32 v65, v64, v64
	v_add_f32_e32 v64, v65, v69
	v_mul_f32_e32 v65, v73, v73
	v_fmac_f32_e32 v65, v72, v72
	v_add_f32_e32 v64, v65, v64
	ds_bpermute_b32 v65, v162, v64
	s_waitcnt lgkmcnt(0)
	v_add_f32_e32 v64, v64, v65
	ds_bpermute_b32 v65, v163, v64
	v_cvt_pk_bf16_f32 v69, v72, v73
	s_nop 0
	global_store_dwordx4 v[76:77], v[66:69], off offset:256
	s_and_saveexec_b64 s[18:19], s[2:3]
	s_cbranch_execz .LBB0_991
	v_lshlrev_b64 v[66:67], 6, v[160:161]
	v_lshl_add_u64 v[66:67], s[40:41], 0, v[66:67]
	v_lshl_add_u64 v[66:67], s[16:17], 2, v[66:67]
	s_lshl_b32 s90, s35, 2
	v_lshl_add_u64 v[66:67], v[66:67], 0, s[90:91]
	s_waitcnt lgkmcnt(0)
	v_add_f32_e32 v64, v64, v65
	global_store_dword v[66:67], v64, off
.LBB0_991:
	s_or_b64 exec, exec, s[18:19]
	v_or_b32_e32 v112, 32, v136
	v_ashrrev_i32_e32 v113, 31, v112
	v_readlane_b32 s56, v252, 12
	s_waitcnt lgkmcnt(0)
	v_lshlrev_b64 v[64:65], 12, v[112:113]
	v_readlane_b32 s57, v252, 13
	s_waitcnt vmcnt(10)
	v_add_f32_e32 v60, v60, v108
	v_add_f32_e32 v104, v56, v104
	v_lshl_add_u64 v[64:65], s[56:57], 0, v[64:65]
	v_lshl_add_u64 v[68:69], v[200:201], 2, v[64:65]
	global_load_dwordx4 v[72:75], v[68:69], off offset:16
	global_load_dwordx4 v[76:79], v[68:69], off
	global_load_dwordx4 v[64:67], v[68:69], off offset:528
	s_nop 0
	global_load_dwordx4 v[68:71], v[68:69], off offset:512
	v_add_f32_e32 v61, v61, v109
	v_add_f32_e32 v105, v57, v105
	v_add_f32_e32 v106, v58, v106
	v_add_f32_e32 v58, v63, v111
	v_add_f32_e32 v63, v59, v107
	v_cvt_pk_bf16_f32 v56, v60, v61
	v_add_f32_e32 v62, v62, v110
	v_mul_f32_e32 v59, v61, v61
	v_fmac_f32_e32 v59, v60, v60
	v_cvt_pk_bf16_f32 v57, v62, v58
	v_lshlrev_b64 v[114:115], 11, v[136:137]
	v_mul_f32_e32 v58, v58, v58
	v_fmac_f32_e32 v58, v62, v62
	v_add_f32_e32 v59, v59, v58
	v_cvt_pk_bf16_f32 v58, v104, v105
	s_waitcnt vmcnt(12)
	v_add_f32_e32 v52, v52, v100
	v_add_f32_e32 v53, v53, v101
	v_mul_f32_e32 v60, v105, v105
	v_fmac_f32_e32 v60, v104, v104
	v_add_f32_e32 v60, v59, v60
	v_cvt_pk_bf16_f32 v59, v106, v63
	v_add_f32_e32 v54, v54, v102
	v_add_f32_e32 v55, v55, v103
	v_mul_f32_e32 v61, v63, v63
	v_fmac_f32_e32 v61, v106, v106
	v_add_f32_e32 v62, v61, v60
	v_lshl_add_u64 v[60:61], s[42:43], 0, v[114:115]
	v_lshl_add_u64 v[60:61], v[200:201], 1, v[60:61]
	global_store_dwordx4 v[60:61], v[56:59], off
	v_add_f32_e32 v48, v48, v96
	v_add_f32_e32 v49, v49, v97
	v_add_f32_e32 v56, v50, v98
	v_add_f32_e32 v57, v51, v99
	v_cvt_pk_bf16_f32 v50, v52, v53
	v_readlane_b32 s58, v252, 14
	v_readlane_b32 s59, v252, 15
	v_mul_f32_e32 v51, v53, v53
	v_fmac_f32_e32 v51, v52, v52
	v_add_f32_e32 v52, v51, v62
	v_cvt_pk_bf16_f32 v51, v54, v55
	v_readlane_b32 s60, v252, 16
	v_readlane_b32 s61, v252, 17
	v_mul_f32_e32 v53, v55, v55
	v_fmac_f32_e32 v53, v54, v54
	v_add_f32_e32 v53, v53, v52
	v_cvt_pk_bf16_f32 v52, v48, v49
	v_readlane_b32 s62, v252, 18
	v_mul_f32_e32 v49, v49, v49
	v_fmac_f32_e32 v49, v48, v48
	v_add_f32_e32 v48, v49, v53
	v_mul_f32_e32 v49, v57, v57
	v_fmac_f32_e32 v49, v56, v56
	v_add_f32_e32 v48, v49, v48
	ds_bpermute_b32 v49, v162, v48
	v_readlane_b32 s63, v252, 19
	v_cvt_pk_bf16_f32 v53, v56, v57
	v_readlane_b32 s64, v252, 20
	s_waitcnt lgkmcnt(0)
	v_add_f32_e32 v48, v48, v49
	ds_bpermute_b32 v49, v163, v48
	v_readlane_b32 s65, v252, 21
	v_readlane_b32 s66, v252, 22
	v_readlane_b32 s67, v252, 23
	v_readlane_b32 s68, v252, 24
	v_readlane_b32 s69, v252, 25
	v_readlane_b32 s70, v252, 26
	v_readlane_b32 s71, v252, 27
	global_store_dwordx4 v[60:61], v[50:53], off offset:256
	s_and_saveexec_b64 s[18:19], s[2:3]
	s_cbranch_execz .LBB0_993
	v_lshlrev_b64 v[50:51], 6, v[136:137]
	v_lshl_add_u64 v[50:51], s[40:41], 0, v[50:51]
	v_lshl_add_u64 v[50:51], s[16:17], 2, v[50:51]
	s_lshl_b32 s90, s35, 2
	v_lshl_add_u64 v[50:51], v[50:51], 0, s[90:91]
	s_waitcnt lgkmcnt(0)
	v_add_f32_e32 v48, v48, v49
	global_store_dword v[50:51], v48, off
.LBB0_993:
	s_or_b64 exec, exec, s[18:19]
	v_or_b32_e32 v96, 48, v136
	v_ashrrev_i32_e32 v97, 31, v96
	v_readlane_b32 s56, v252, 12
	s_waitcnt lgkmcnt(0)
	v_lshlrev_b64 v[48:49], 12, v[96:97]
	v_readlane_b32 s57, v252, 13
	s_waitcnt vmcnt(11)
	v_add_f32_e32 v44, v44, v88
	s_waitcnt vmcnt(9)
	v_add_f32_e32 v88, v40, v92
	v_lshl_add_u64 v[48:49], s[56:57], 0, v[48:49]
	v_lshl_add_u64 v[52:53], v[200:201], 2, v[48:49]
	global_load_dwordx4 v[56:59], v[52:53], off offset:16
	global_load_dwordx4 v[60:63], v[52:53], off
	global_load_dwordx4 v[48:51], v[52:53], off offset:528
	s_nop 0
	global_load_dwordx4 v[52:55], v[52:53], off offset:512
	v_add_f32_e32 v45, v45, v89
	v_add_f32_e32 v89, v41, v93
	v_add_f32_e32 v46, v46, v90
	v_add_f32_e32 v90, v42, v94
	v_add_f32_e32 v42, v47, v91
	v_add_f32_e32 v47, v43, v95
	v_cvt_pk_bf16_f32 v40, v44, v45
	v_or_b32_e32 v98, 16, v136
	v_mul_f32_e32 v43, v45, v45
	v_fmac_f32_e32 v43, v44, v44
	v_cvt_pk_bf16_f32 v41, v46, v42
	v_ashrrev_i32_e32 v99, 31, v98
	v_mul_f32_e32 v42, v42, v42
	v_fmac_f32_e32 v42, v46, v46
	v_add_f32_e32 v43, v43, v42
	v_cvt_pk_bf16_f32 v42, v88, v89
	v_lshlrev_b64 v[100:101], 11, v[98:99]
	s_waitcnt vmcnt(12)
	v_add_f32_e32 v36, v36, v84
	v_mul_f32_e32 v44, v89, v89
	v_fmac_f32_e32 v44, v88, v88
	v_add_f32_e32 v44, v43, v44
	v_cvt_pk_bf16_f32 v43, v90, v47
	v_add_f32_e32 v37, v37, v85
	v_add_f32_e32 v38, v38, v86
	v_mul_f32_e32 v45, v47, v47
	v_fmac_f32_e32 v45, v90, v90
	v_add_f32_e32 v46, v45, v44
	v_lshl_add_u64 v[44:45], s[42:43], 0, v[100:101]
	v_lshl_add_u64 v[44:45], v[200:201], 1, v[44:45]
	global_store_dwordx4 v[44:45], v[40:43], off
	v_add_f32_e32 v39, v39, v87
	v_add_f32_e32 v32, v32, v80
	v_add_f32_e32 v40, v34, v82
	v_add_f32_e32 v41, v35, v83
	v_cvt_pk_bf16_f32 v34, v36, v37
	v_add_f32_e32 v33, v33, v81
	v_readlane_b32 s58, v252, 14
	v_mul_f32_e32 v35, v37, v37
	v_fmac_f32_e32 v35, v36, v36
	v_add_f32_e32 v36, v35, v46
	v_cvt_pk_bf16_f32 v35, v38, v39
	v_readlane_b32 s59, v252, 15
	v_and_b32_e32 v42, 0xffff0000, v35
	v_sub_f32_e32 v42, v39, v42
	v_readlane_b32 s60, v252, 16
	v_mul_f32_e32 v37, v39, v39
	v_fmac_f32_e32 v37, v38, v38
	v_add_f32_e32 v37, v37, v36
	v_cvt_pk_bf16_f32 v36, v32, v33
	v_readlane_b32 s61, v252, 17
	v_mul_f32_e32 v33, v33, v33
	v_fmac_f32_e32 v33, v32, v32
	v_add_f32_e32 v32, v33, v37
	v_mul_f32_e32 v33, v41, v41
	v_fmac_f32_e32 v33, v40, v40
	v_add_f32_e32 v32, v33, v32
	ds_bpermute_b32 v33, v162, v32
	v_readlane_b32 s62, v252, 18
	v_cvt_pk_bf16_f32 v37, v40, v41
	v_readlane_b32 s63, v252, 19
	s_waitcnt lgkmcnt(0)
	v_add_f32_e32 v32, v32, v33
	ds_bpermute_b32 v33, v163, v32
	v_lshlrev_b32_e32 v38, 16, v37
	v_sub_f32_e32 v38, v40, v38
	v_and_b32_e32 v39, 0xffff0000, v37
	v_readlane_b32 s64, v252, 20
	v_readlane_b32 s65, v252, 21
	v_readlane_b32 s66, v252, 22
	v_readlane_b32 s67, v252, 23
	v_readlane_b32 s68, v252, 24
	v_readlane_b32 s69, v252, 25
	v_readlane_b32 s70, v252, 26
	v_readlane_b32 s71, v252, 27
	v_sub_f32_e32 v39, v41, v39
	v_cvt_pk_bf16_f32 v38, v38, v39
	global_store_dwordx4 v[44:45], v[34:37], off offset:256
	s_and_saveexec_b64 s[18:19], s[2:3]
	s_cbranch_execz .LBB0_995
	v_lshlrev_b64 v[34:35], 6, v[98:99]
	v_lshl_add_u64 v[34:35], s[40:41], 0, v[34:35]
	v_lshl_add_u64 v[34:35], s[16:17], 2, v[34:35]
	s_lshl_b32 s90, s35, 2
	v_lshl_add_u64 v[34:35], v[34:35], 0, s[90:91]
	s_waitcnt lgkmcnt(0)
	v_add_f32_e32 v32, v32, v33
	global_store_dword v[34:35], v32, off
.LBB0_995:
	s_or_b64 exec, exec, s[18:19]
	s_waitcnt vmcnt(10)
	v_add_f32_e32 v28, v28, v76
	v_add_f32_e32 v34, v24, v72
	v_add_f32_e32 v29, v29, v77
	v_add_f32_e32 v35, v25, v73
	v_add_f32_e32 v36, v26, v74
	v_add_f32_e32 v26, v31, v79
	v_add_f32_e32 v31, v27, v75
	v_cvt_pk_bf16_f32 v24, v28, v29
	v_add_f32_e32 v30, v30, v78
	v_mul_f32_e32 v27, v29, v29
	v_fmac_f32_e32 v27, v28, v28
	v_cvt_pk_bf16_f32 v25, v30, v26
	s_waitcnt lgkmcnt(0)
	v_lshlrev_b64 v[32:33], 11, v[112:113]
	v_mul_f32_e32 v26, v26, v26
	v_fmac_f32_e32 v26, v30, v30
	v_add_f32_e32 v27, v27, v26
	v_cvt_pk_bf16_f32 v26, v34, v35
	s_waitcnt vmcnt(8)
	v_add_f32_e32 v20, v20, v68
	v_add_f32_e32 v21, v21, v69
	v_mul_f32_e32 v28, v35, v35
	v_fmac_f32_e32 v28, v34, v34
	v_add_f32_e32 v28, v27, v28
	v_cvt_pk_bf16_f32 v27, v36, v31
	v_add_f32_e32 v22, v22, v70
	v_add_f32_e32 v23, v23, v71
	v_mul_f32_e32 v29, v31, v31
	v_fmac_f32_e32 v29, v36, v36
	v_add_f32_e32 v30, v29, v28
	v_lshl_add_u64 v[28:29], s[42:43], 0, v[32:33]
	v_lshl_add_u64 v[28:29], v[200:201], 1, v[28:29]
	global_store_dwordx4 v[28:29], v[24:27], off
	v_add_f32_e32 v16, v16, v64
	v_add_f32_e32 v17, v17, v65
	v_add_f32_e32 v24, v18, v66
	v_add_f32_e32 v25, v19, v67
	v_cvt_pk_bf16_f32 v18, v20, v21
	s_nop 0
	s_nop 0
	v_mul_f32_e32 v19, v21, v21
	v_fmac_f32_e32 v19, v20, v20
	v_add_f32_e32 v20, v19, v30
	v_cvt_pk_bf16_f32 v19, v22, v23
	s_nop 0
	v_and_b32_e32 v26, 0xffff0000, v19
	v_sub_f32_e32 v26, v23, v26
	s_nop 0
	v_mul_f32_e32 v21, v23, v23
	v_fmac_f32_e32 v21, v22, v22
	v_add_f32_e32 v21, v21, v20
	v_cvt_pk_bf16_f32 v20, v16, v17
	s_nop 0
	v_mul_f32_e32 v17, v17, v17
	v_fmac_f32_e32 v17, v16, v16
	v_add_f32_e32 v16, v17, v21
	v_mul_f32_e32 v17, v25, v25
	v_fmac_f32_e32 v17, v24, v24
	v_add_f32_e32 v16, v17, v16
	ds_bpermute_b32 v17, v162, v16
	s_waitcnt lgkmcnt(0)
	v_add_f32_e32 v16, v16, v17
	ds_bpermute_b32 v17, v163, v16
	v_cvt_pk_bf16_f32 v21, v24, v25
	s_nop 0
	v_lshlrev_b32_e32 v22, 16, v21
	v_sub_f32_e32 v22, v24, v22
	v_and_b32_e32 v23, 0xffff0000, v21
	v_sub_f32_e32 v23, v25, v23
	v_cvt_pk_bf16_f32 v22, v22, v23
	global_store_dwordx4 v[28:29], v[18:21], off offset:256
	s_and_saveexec_b64 s[18:19], s[2:3]
	s_cbranch_execz .LBB0_997
	v_lshlrev_b64 v[18:19], 6, v[112:113]
	v_lshl_add_u64 v[18:19], s[40:41], 0, v[18:19]
	v_lshl_add_u64 v[18:19], s[16:17], 2, v[18:19]
	s_lshl_b32 s90, s35, 2
	v_lshl_add_u64 v[18:19], v[18:19], 0, s[90:91]
	s_waitcnt lgkmcnt(0)
	v_add_f32_e32 v16, v16, v17
	global_store_dword v[18:19], v16, off
.LBB0_997:
	s_or_b64 exec, exec, s[18:19]
	s_waitcnt vmcnt(6)
	v_add_f32_e32 v12, v12, v60
	v_add_f32_e32 v18, v8, v56
	v_add_f32_e32 v13, v13, v61
	v_add_f32_e32 v19, v9, v57
	v_add_f32_e32 v20, v10, v58
	v_add_f32_e32 v10, v15, v63
	v_add_f32_e32 v15, v11, v59
	v_cvt_pk_bf16_f32 v8, v12, v13
	v_add_f32_e32 v14, v14, v62
	v_mul_f32_e32 v11, v13, v13
	v_fmac_f32_e32 v11, v12, v12
	v_cvt_pk_bf16_f32 v9, v14, v10
	s_waitcnt lgkmcnt(0)
	v_lshlrev_b64 v[16:17], 11, v[96:97]
	v_mul_f32_e32 v10, v10, v10
	v_fmac_f32_e32 v10, v14, v14
	v_add_f32_e32 v11, v11, v10
	v_cvt_pk_bf16_f32 v10, v18, v19
	s_waitcnt vmcnt(4)
	v_add_f32_e32 v4, v4, v52
	v_add_f32_e32 v5, v5, v53
	v_mul_f32_e32 v12, v19, v19
	v_fmac_f32_e32 v12, v18, v18
	v_add_f32_e32 v12, v11, v12
	v_cvt_pk_bf16_f32 v11, v20, v15
	v_add_f32_e32 v6, v6, v54
	v_add_f32_e32 v7, v7, v55
	v_mul_f32_e32 v13, v15, v15
	v_fmac_f32_e32 v13, v20, v20
	v_add_f32_e32 v14, v13, v12
	v_lshl_add_u64 v[12:13], s[42:43], 0, v[16:17]
	v_lshl_add_u64 v[12:13], v[200:201], 1, v[12:13]
	global_store_dwordx4 v[12:13], v[8:11], off
	v_add_f32_e32 v0, v0, v48
	v_add_f32_e32 v1, v1, v49
	v_add_f32_e32 v8, v2, v50
	v_add_f32_e32 v9, v3, v51
	v_cvt_pk_bf16_f32 v2, v4, v5
	s_nop 0
	s_nop 0
	v_mul_f32_e32 v3, v5, v5
	v_fmac_f32_e32 v3, v4, v4
	v_add_f32_e32 v4, v3, v14
	v_cvt_pk_bf16_f32 v3, v6, v7
	s_nop 0
	v_and_b32_e32 v10, 0xffff0000, v3
	v_sub_f32_e32 v10, v7, v10
	s_nop 0
	v_mul_f32_e32 v5, v7, v7
	v_fmac_f32_e32 v5, v6, v6
	v_add_f32_e32 v5, v5, v4
	v_cvt_pk_bf16_f32 v4, v0, v1
	s_nop 0
	v_mul_f32_e32 v1, v1, v1
	v_fmac_f32_e32 v1, v0, v0
	v_add_f32_e32 v0, v1, v5
	v_mul_f32_e32 v1, v9, v9
	v_fmac_f32_e32 v1, v8, v8
	v_add_f32_e32 v0, v1, v0
	ds_bpermute_b32 v1, v162, v0
	s_waitcnt lgkmcnt(0)
	v_add_f32_e32 v0, v0, v1
	ds_bpermute_b32 v1, v163, v0
	v_cvt_pk_bf16_f32 v5, v8, v9
	s_nop 0
	v_lshlrev_b32_e32 v6, 16, v5
	v_sub_f32_e32 v6, v8, v6
	v_and_b32_e32 v7, 0xffff0000, v5
	v_sub_f32_e32 v7, v9, v7
	v_cvt_pk_bf16_f32 v6, v6, v7
	global_store_dwordx4 v[12:13], v[2:5], off offset:256
	s_and_saveexec_b64 s[18:19], s[2:3]
	s_cbranch_execz .LBB0_999
	v_lshlrev_b64 v[2:3], 6, v[96:97]
	v_lshl_add_u64 v[2:3], s[40:41], 0, v[2:3]
	v_lshl_add_u64 v[2:3], s[16:17], 2, v[2:3]
	s_lshl_b32 s90, s35, 2
	v_lshl_add_u64 v[2:3], v[2:3], 0, s[90:91]
	s_waitcnt lgkmcnt(0)
	v_add_f32_e32 v0, v0, v1
	global_store_dword v[2:3], v0, off

.LBB0_1068:
	s_lshl_b32 s9, s54, 8
	s_add_i32 s9, s9, s27
	v_or_b32_e32 v154, s9, v157
	v_ashrrev_i32_e32 v155, 31, v154
	v_or_b32_e32 v150, 16, v154
	v_lshlrev_b64 v[146:147], 6, v[154:155]
	v_ashrrev_i32_e32 v151, 31, v150
	v_or_b32_e32 v158, 32, v154
	v_lshl_add_u64 v[146:147], v[136:137], 0, v[146:147]
	v_lshlrev_b64 v[150:151], 6, v[150:151]
	v_ashrrev_i32_e32 v159, 31, v158
	global_load_dwordx4 v[146:149], v[146:147], off
	v_lshl_add_u64 v[150:151], v[136:137], 0, v[150:151]
	v_lshlrev_b64 v[158:159], 6, v[158:159]
	global_load_dwordx4 v[150:153], v[150:151], off
	v_lshl_add_u64 v[158:159], v[136:137], 0, v[158:159]
	global_load_dwordx4 v[178:181], v[158:159], off
	v_or_b32_e32 v158, 48, v154
	v_ashrrev_i32_e32 v159, 31, v158
	v_lshlrev_b64 v[158:159], 6, v[158:159]
	v_lshl_add_u64 v[158:159], v[136:137], 0, v[158:159]
	global_load_dwordx4 v[190:193], v[158:159], off
	v_add_u32_e32 v158, 0x80, v154
	v_ashrrev_i32_e32 v159, 31, v158
	v_lshlrev_b64 v[158:159], 6, v[158:159]
	v_lshl_add_u64 v[158:159], v[136:137], 0, v[158:159]
	global_load_dwordx4 v[194:197], v[158:159], off
	v_add_u32_e32 v158, 0x90, v154
	v_ashrrev_i32_e32 v159, 31, v158
	v_lshlrev_b64 v[158:159], 6, v[158:159]
	v_lshl_add_u64 v[158:159], v[136:137], 0, v[158:159]
	global_load_dwordx4 v[198:201], v[158:159], off
	v_add_u32_e32 v158, 0xa0, v154
	v_add_u32_e32 v154, 0xb0, v154
	v_ashrrev_i32_e32 v159, 31, v158
	v_ashrrev_i32_e32 v155, 31, v154
	v_lshlrev_b64 v[158:159], 6, v[158:159]
	v_lshlrev_b64 v[154:155], 6, v[154:155]
	v_lshl_add_u64 v[158:159], v[136:137], 0, v[158:159]
	v_lshl_add_u64 v[154:155], v[136:137], 0, v[154:155]
	global_load_dwordx4 v[202:205], v[158:159], off
	global_load_dwordx4 v[206:209], v[154:155], off
	v_and_b32_e32 v156, 64, v213
	v_xor_b32_e32 v145, 16, v213
	v_add_u32_e32 v156, 64, v156
	v_cmp_lt_i32_e32 vcc, v145, v156
	s_mov_b64 s[56:57], s[44:45]
	s_mov_b32 s55, s72
	v_cndmask_b32_e32 v145, v213, v145, vcc
	v_lshlrev_b32_e32 v165, 2, v145
	v_xor_b32_e32 v145, 32, v213
	v_cmp_lt_i32_e32 vcc, v145, v156
	s_waitcnt vmcnt(0)
	v_mov_b32_e32 v154, v147
	v_mov_b32_e32 v155, v148
	v_mov_b32_e32 v147, v149
	v_pk_add_f32 v[162:163], v[154:155], v[146:147]
	v_mov_b32_e32 v146, v151
	v_mov_b32_e32 v147, v152
	v_mov_b32_e32 v151, v153
	v_pk_add_f32 v[166:167], v[146:147], v[150:151]
	v_mov_b32_e32 v146, v179
	v_mov_b32_e32 v147, v180
	v_mov_b32_e32 v179, v181
	v_pk_add_f32 v[154:155], v[146:147], v[178:179]
	v_mov_b32_e32 v178, v166
	v_mov_b32_e32 v179, v162
	v_mov_b32_e32 v162, v167
	v_pk_add_f32 v[162:163], v[178:179], v[162:163]
	ds_bpermute_b32 v167, v165, v163
	ds_bpermute_b32 v166, v165, v162
	v_cndmask_b32_e32 v145, v213, v145, vcc
	v_lshlrev_b32_e32 v145, 2, v145
	v_mov_b32_e32 v146, v191
	v_mov_b32_e32 v147, v192
	s_waitcnt lgkmcnt(0)
	v_pk_add_f32 v[162:163], v[162:163], v[166:167]
	ds_bpermute_b32 v167, v145, v163
	ds_bpermute_b32 v166, v145, v162
	v_mov_b32_e32 v191, v193
	v_pk_add_f32 v[158:159], v[146:147], v[190:191]
	v_mov_b32_e32 v146, v195
	v_mov_b32_e32 v147, v196
	s_waitcnt lgkmcnt(0)
	v_pk_add_f32 v[166:167], v[162:163], v[166:167]
	v_mov_b64_e32 v[162:163], s[64:65]
	v_pk_fma_f32 v[166:167], v[166:167], s[28:29], v[162:163] op_sel_hi:[1,0,0]
	v_mov_b32_e32 v195, v197
	v_mul_f32_e32 v156, 0x4b800000, v167
	v_cmp_gt_f32_e64 s[0:1], s52, v167
	v_cmp_gt_f32_e32 vcc, s52, v166
	v_pk_add_f32 v[150:151], v[146:147], v[194:195]
	v_cndmask_b32_e64 v156, v167, v156, s[0:1]
	v_rsq_f32_e32 v156, v156
	v_mov_b32_e32 v146, v199
	v_mov_b32_e32 v147, v200
	v_mov_b32_e32 v199, v201
	v_mul_f32_e32 v160, 0x45800000, v156
	v_cndmask_b32_e64 v160, v156, v160, s[0:1]
	v_mul_f32_e32 v156, 0x4b800000, v166
	v_cndmask_b32_e32 v156, v166, v156, vcc
	v_rsq_f32_e32 v156, v156
	v_pk_add_f32 v[152:153], v[146:147], v[198:199]
	v_mov_b32_e32 v146, v203
	v_mov_b32_e32 v147, v204
	v_mul_f32_e32 v166, 0x45800000, v156
	v_mov_b32_e32 v203, v205
	v_mov_b32_e32 v148, v207
	v_mov_b32_e32 v149, v208
	v_mov_b32_e32 v207, v209
	v_cndmask_b32_e32 v156, v156, v166, vcc
	v_mov_b32_e32 v166, v158
	v_mov_b32_e32 v167, v154
	v_mov_b32_e32 v154, v159
	v_pk_add_f32 v[146:147], v[146:147], v[202:203]
	v_pk_add_f32 v[148:149], v[148:149], v[206:207]
	v_pk_add_f32 v[154:155], v[166:167], v[154:155]
	v_mov_b32_e32 v166, v152
	v_mov_b32_e32 v167, v150
	v_mov_b32_e32 v150, v153
	v_pk_add_f32 v[150:151], v[166:167], v[150:151]
	v_mov_b32_e32 v166, v148
	v_mov_b32_e32 v167, v146
	v_mov_b32_e32 v146, v149
	v_pk_add_f32 v[146:147], v[166:167], v[146:147]
	ds_bpermute_b32 v159, v165, v155
	ds_bpermute_b32 v158, v165, v154
	ds_bpermute_b32 v153, v165, v151
	ds_bpermute_b32 v152, v165, v150
	ds_bpermute_b32 v149, v165, v147
	ds_bpermute_b32 v148, v165, v146
	s_waitcnt lgkmcnt(4)
	v_pk_add_f32 v[154:155], v[154:155], v[158:159]
	ds_bpermute_b32 v159, v145, v155
	s_waitcnt lgkmcnt(3)
	v_pk_add_f32 v[150:151], v[150:151], v[152:153]
	ds_bpermute_b32 v158, v145, v154
	s_waitcnt lgkmcnt(2)
	v_pk_add_f32 v[146:147], v[146:147], v[148:149]
	ds_bpermute_b32 v153, v145, v151
	ds_bpermute_b32 v152, v145, v150
	ds_bpermute_b32 v149, v145, v147
	ds_bpermute_b32 v148, v145, v146
	s_waitcnt lgkmcnt(4)
	v_pk_add_f32 v[154:155], v[154:155], v[158:159]
	s_waitcnt lgkmcnt(2)
	v_pk_add_f32 v[150:151], v[150:151], v[152:153]
	v_pk_fma_f32 v[154:155], v[154:155], s[28:29], v[162:163] op_sel_hi:[1,0,0]
	s_waitcnt lgkmcnt(0)
	v_pk_add_f32 v[146:147], v[146:147], v[148:149]
	v_pk_fma_f32 v[150:151], v[150:151], s[28:29], v[162:163] op_sel_hi:[1,0,0]
	v_pk_fma_f32 v[146:147], v[146:147], s[28:29], v[162:163] op_sel_hi:[1,0,0]
	v_mul_f32_e32 v158, 0x4b800000, v155
	v_cmp_gt_f32_e64 s[0:1], s52, v155
	v_mul_f32_e32 v152, 0x4b800000, v151
	s_nop 0
	v_cndmask_b32_e64 v155, v155, v158, s[0:1]
	v_rsq_f32_e32 v155, v155
	v_mul_f32_e32 v145, 0x4b800000, v147
	v_mul_f32_e32 v158, 0x45800000, v155
	v_cndmask_b32_e64 v158, v155, v158, s[0:1]
	v_cmp_gt_f32_e64 s[0:1], s52, v151
	v_cmp_gt_f32_e32 vcc, s52, v154
	s_nop 0
	v_cndmask_b32_e64 v151, v151, v152, s[0:1]
	v_rsq_f32_e32 v151, v151
	v_mul_f32_e32 v155, 0x4b800000, v154
	v_mul_f32_e32 v152, 0x45800000, v151
	v_cndmask_b32_e64 v152, v151, v152, s[0:1]
	v_cmp_gt_f32_e64 s[0:1], s52, v147
	s_nop 1
	v_cndmask_b32_e64 v145, v147, v145, s[0:1]
	v_rsq_f32_e32 v145, v145
	v_cndmask_b32_e32 v154, v154, v155, vcc
	v_mul_f32_e32 v236, 0xbfb8aa3b, v160
	v_mul_f32_e32 v237, v160, v160
	v_mul_f32_e32 v220, v236, v124
	v_mul_f32_e32 v222, v236, v125
	v_mul_f32_e32 v224, v236, v126
	v_mul_f32_e32 v226, v236, v127
	v_mul_f32_e32 v221, v124, v120
	v_mul_f32_e32 v223, v125, v121
	v_mul_f32_e32 v225, v126, v122
	v_mul_f32_e32 v227, v127, v123
	v_exp_f32_e32 v220, v220
	v_exp_f32_e32 v222, v222
	v_exp_f32_e32 v224, v224
	v_exp_f32_e32 v226, v226
	v_mul_f32_e32 v221, v237, v221
	v_mul_f32_e32 v223, v237, v223
	v_mul_f32_e32 v225, v237, v225
	v_mul_f32_e32 v227, v237, v227
	v_add_f32_e32 v220, 1.0, v220
	v_add_f32_e32 v222, 1.0, v222
	v_add_f32_e32 v224, 1.0, v224
	v_add_f32_e32 v226, 1.0, v226
	v_rcp_f32_e32 v220, v220
	v_rcp_f32_e32 v222, v222
	v_rcp_f32_e32 v224, v224
	v_rcp_f32_e32 v226, v226
	v_mul_f32_e32 v124, v221, v220
	v_mul_f32_e32 v125, v223, v222
	v_mul_f32_e32 v126, v225, v224
	v_mul_f32_e32 v122, v227, v226
	v_mul_f32_e32 v147, 0x45800000, v145
	v_cndmask_b32_e64 v148, v145, v147, s[0:1]
	s_lshl_b32 s0, s36, 7
	s_or_b32 s0, s0, s34
	s_ashr_i32 s11, s0, 6
	s_ashr_i32 s0, s9, 8
	s_mul_i32 s0, s0, 44
	s_add_i32 s0, s0, s11
	s_lshl_b32 s0, s0, 1
	s_or_b32 s0, s0, s87
	s_ashr_i32 s1, s0, 31
	s_lshl_b64 s[0:1], s[0:1], 14
	v_rsq_f32_e32 v154, v154
	s_nop 0
	v_mul_f32_e32 v155, 0x45800000, v154
	v_cndmask_b32_e32 v154, v154, v155, vcc
	v_cmp_gt_f32_e32 vcc, s52, v150
	v_mul_f32_e32 v151, 0x4b800000, v150
	s_nop 0
	v_cndmask_b32_e32 v150, v150, v151, vcc
	v_rsq_f32_e32 v150, v150
	s_addk_i32 s9, 0x80
	v_mul_f32_e32 v151, 0x45800000, v150
	v_cndmask_b32_e32 v150, v150, v151, vcc
	v_cmp_gt_f32_e32 vcc, s52, v146
	v_mul_f32_e32 v145, 0x4b800000, v146
	s_nop 0
	v_cndmask_b32_e32 v145, v146, v145, vcc
	v_rsq_f32_e32 v145, v145
	v_mul_f32_e32 v228, v236, v116
	v_mul_f32_e32 v230, v236, v117
	v_mul_f32_e32 v232, v236, v118
	v_mul_f32_e32 v234, v236, v119
	v_mul_f32_e32 v229, v116, v112
	v_mul_f32_e32 v231, v117, v113
	v_mul_f32_e32 v233, v118, v114
	v_mul_f32_e32 v235, v119, v115
	v_exp_f32_e32 v228, v228
	v_exp_f32_e32 v230, v230
	v_exp_f32_e32 v232, v232
	v_exp_f32_e32 v234, v234
	v_mul_f32_e32 v229, v237, v229
	v_mul_f32_e32 v231, v237, v231
	v_mul_f32_e32 v233, v237, v233
	v_mul_f32_e32 v235, v237, v235
	v_add_f32_e32 v228, 1.0, v228
	v_add_f32_e32 v230, 1.0, v230
	v_add_f32_e32 v232, 1.0, v232
	v_add_f32_e32 v234, 1.0, v234
	v_rcp_f32_e32 v228, v228
	v_rcp_f32_e32 v230, v230
	v_rcp_f32_e32 v232, v232
	v_rcp_f32_e32 v234, v234
	v_mul_f32_e32 v116, v229, v228
	v_mul_f32_e32 v117, v231, v230
	v_mul_f32_e32 v118, v233, v232
	v_mul_f32_e32 v112, v235, v234
	v_cvt_pk_bf16_f32 v114, v124, v125
	v_cvt_pk_bf16_f32 v115, v126, v122
	v_cvt_pk_bf16_f32 v116, v116, v117
	v_mul_f32_e32 v146, 0x45800000, v145
	v_cndmask_b32_e32 v146, v145, v146, vcc
	v_mov_b32_e32 v145, v169
	v_cvt_pk_bf16_f32 v117, v118, v112
	v_lshl_add_u64 v[112:113], v[138:139], 0, s[0:1]
	global_store_dwordx4 v[112:113], v[114:117], off
	s_ashr_i32 s0, s9, 8
	s_mul_i32 s0, s0, 44
	s_add_i32 s0, s0, s11
	s_lshl_b32 s0, s0, 1
	s_or_b32 s0, s0, s87
	s_ashr_i32 s1, s0, 31
	s_and_b32 s9, s9, 0xc0
	s_lshl_b64 s[0:1], s[0:1], 14
	s_add_u32 s0, s48, s0
	s_addc_u32 s1, s49, s1
	s_andn2_b64 vcc, exec, s[2:3]
	v_mul_f32_e32 v238, 0xbfb8aa3b, v156
	v_mul_f32_e32 v239, v156, v156
	v_mul_f32_e32 v220, v238, v108
	v_mul_f32_e32 v222, v238, v109
	v_mul_f32_e32 v224, v238, v110
	v_mul_f32_e32 v226, v238, v111
	v_mul_f32_e32 v221, v108, v104
	v_mul_f32_e32 v223, v109, v105
	v_mul_f32_e32 v225, v110, v106
	v_mul_f32_e32 v227, v111, v107
	v_exp_f32_e32 v220, v220
	v_exp_f32_e32 v222, v222
	v_exp_f32_e32 v224, v224
	v_exp_f32_e32 v226, v226
	v_mul_f32_e32 v221, v239, v221
	v_mul_f32_e32 v223, v239, v223
	v_mul_f32_e32 v225, v239, v225
	v_mul_f32_e32 v227, v239, v227
	v_add_f32_e32 v220, 1.0, v220
	v_add_f32_e32 v222, 1.0, v222
	v_add_f32_e32 v224, 1.0, v224
	v_add_f32_e32 v226, 1.0, v226
	v_rcp_f32_e32 v220, v220
	v_rcp_f32_e32 v222, v222
	v_rcp_f32_e32 v224, v224
	v_rcp_f32_e32 v226, v226
	v_mul_f32_e32 v108, v221, v220
	v_mul_f32_e32 v109, v223, v222
	v_mul_f32_e32 v110, v225, v224
	v_mul_f32_e32 v106, v227, v226
	s_nop 0
	s_nop 0
	s_nop 0
	v_mul_f32_e32 v228, v238, v100
	v_mul_f32_e32 v230, v238, v101
	v_mul_f32_e32 v232, v238, v102
	v_mul_f32_e32 v234, v238, v103
	v_mul_f32_e32 v229, v100, v96
	v_mul_f32_e32 v231, v101, v97
	v_mul_f32_e32 v233, v102, v98
	v_mul_f32_e32 v235, v103, v99
	v_exp_f32_e32 v228, v228
	v_exp_f32_e32 v230, v230
	v_exp_f32_e32 v232, v232
	v_exp_f32_e32 v234, v234
	v_mul_f32_e32 v229, v239, v229
	v_mul_f32_e32 v231, v239, v231
	v_mul_f32_e32 v233, v239, v233
	v_mul_f32_e32 v235, v239, v235
	v_add_f32_e32 v228, 1.0, v228
	v_add_f32_e32 v230, 1.0, v230
	v_add_f32_e32 v232, 1.0, v232
	v_add_f32_e32 v234, 1.0, v234
	v_rcp_f32_e32 v228, v228
	v_rcp_f32_e32 v230, v230
	v_rcp_f32_e32 v232, v232
	v_rcp_f32_e32 v234, v234
	v_mul_f32_e32 v100, v229, v228
	v_mul_f32_e32 v101, v231, v230
	v_mul_f32_e32 v102, v233, v232
	v_mul_f32_e32 v99, v235, v234
	s_nop 0
	v_cvt_pk_bf16_f32 v96, v108, v109
	v_cvt_pk_bf16_f32 v97, v110, v106
	v_cvt_pk_bf16_f32 v98, v100, v101
	v_cvt_pk_bf16_f32 v99, v102, v99
	global_store_dwordx4 v[112:113], v[96:99], off offset:1024
	s_nop 1
	s_nop 0
	s_nop 0
	v_mul_f32_e32 v240, 0xbfb8aa3b, v158
	v_mul_f32_e32 v241, v158, v158
	v_mul_f32_e32 v220, v240, v92
	v_mul_f32_e32 v222, v240, v93
	v_mul_f32_e32 v224, v240, v94
	v_mul_f32_e32 v226, v240, v95
	v_mul_f32_e32 v221, v92, v88
	v_mul_f32_e32 v223, v93, v89
	v_mul_f32_e32 v225, v94, v90
	v_mul_f32_e32 v227, v95, v91
	v_exp_f32_e32 v220, v220
	v_exp_f32_e32 v222, v222
	v_exp_f32_e32 v224, v224
	v_exp_f32_e32 v226, v226
	v_mul_f32_e32 v221, v241, v221
	v_mul_f32_e32 v223, v241, v223
	v_mul_f32_e32 v225, v241, v225
	v_mul_f32_e32 v227, v241, v227
	v_add_f32_e32 v220, 1.0, v220
	v_add_f32_e32 v222, 1.0, v222
	v_add_f32_e32 v224, 1.0, v224
	v_add_f32_e32 v226, 1.0, v226
	v_rcp_f32_e32 v220, v220
	v_rcp_f32_e32 v222, v222
	v_rcp_f32_e32 v224, v224
	v_rcp_f32_e32 v226, v226
	v_mul_f32_e32 v92, v221, v220
	v_mul_f32_e32 v93, v223, v222
	v_mul_f32_e32 v94, v225, v224
	v_mul_f32_e32 v90, v227, v226
	s_nop 0
	s_nop 0
	s_nop 0
	v_mul_f32_e32 v228, v240, v84
	v_mul_f32_e32 v230, v240, v85
	v_mul_f32_e32 v232, v240, v86
	v_mul_f32_e32 v234, v240, v87
	v_mul_f32_e32 v229, v84, v80
	v_mul_f32_e32 v231, v85, v81
	v_mul_f32_e32 v233, v86, v82
	v_mul_f32_e32 v235, v87, v83
	v_exp_f32_e32 v228, v228
	v_exp_f32_e32 v230, v230
	v_exp_f32_e32 v232, v232
	v_exp_f32_e32 v234, v234
	v_mul_f32_e32 v229, v241, v229
	v_mul_f32_e32 v231, v241, v231
	v_mul_f32_e32 v233, v241, v233
	v_mul_f32_e32 v235, v241, v235
	v_add_f32_e32 v228, 1.0, v228
	v_add_f32_e32 v230, 1.0, v230
	v_add_f32_e32 v232, 1.0, v232
	v_add_f32_e32 v234, 1.0, v234
	v_rcp_f32_e32 v228, v228
	v_rcp_f32_e32 v230, v230
	v_rcp_f32_e32 v232, v232
	v_rcp_f32_e32 v234, v234
	v_mul_f32_e32 v84, v229, v228
	v_mul_f32_e32 v85, v231, v230
	v_mul_f32_e32 v86, v233, v232
	v_mul_f32_e32 v83, v235, v234
	s_nop 0
	v_cvt_pk_bf16_f32 v80, v92, v93
	v_cvt_pk_bf16_f32 v81, v94, v90
	v_cvt_pk_bf16_f32 v82, v84, v85
	v_cvt_pk_bf16_f32 v83, v86, v83
	global_store_dwordx4 v[112:113], v[80:83], off offset:2048
	s_nop 1
	s_nop 0
	s_nop 0
	v_mul_f32_e32 v242, 0xbfb8aa3b, v154
	v_mul_f32_e32 v243, v154, v154
	v_mul_f32_e32 v220, v242, v76
	v_mul_f32_e32 v222, v242, v77
	v_mul_f32_e32 v224, v242, v78
	v_mul_f32_e32 v226, v242, v79
	v_mul_f32_e32 v221, v76, v72
	v_mul_f32_e32 v223, v77, v73
	v_mul_f32_e32 v225, v78, v74
	v_mul_f32_e32 v227, v79, v75
	v_exp_f32_e32 v220, v220
	v_exp_f32_e32 v222, v222
	v_exp_f32_e32 v224, v224
	v_exp_f32_e32 v226, v226
	v_mul_f32_e32 v221, v243, v221
	v_mul_f32_e32 v223, v243, v223
	v_mul_f32_e32 v225, v243, v225
	v_mul_f32_e32 v227, v243, v227
	v_add_f32_e32 v220, 1.0, v220
	v_add_f32_e32 v222, 1.0, v222
	v_add_f32_e32 v224, 1.0, v224
	v_add_f32_e32 v226, 1.0, v226
	v_rcp_f32_e32 v220, v220
	v_rcp_f32_e32 v222, v222
	v_rcp_f32_e32 v224, v224
	v_rcp_f32_e32 v226, v226
	v_mul_f32_e32 v76, v221, v220
	v_mul_f32_e32 v77, v223, v222
	v_mul_f32_e32 v78, v225, v224
	v_mul_f32_e32 v74, v227, v226
	s_nop 0
	s_nop 0
	s_nop 0
	v_mul_f32_e32 v228, v242, v68
	v_mul_f32_e32 v230, v242, v69
	v_mul_f32_e32 v232, v242, v70
	v_mul_f32_e32 v234, v242, v71
	v_mul_f32_e32 v229, v68, v64
	v_mul_f32_e32 v231, v69, v65
	v_mul_f32_e32 v233, v70, v66
	v_mul_f32_e32 v235, v71, v67
	v_exp_f32_e32 v228, v228
	v_exp_f32_e32 v230, v230
	v_exp_f32_e32 v232, v232
	v_exp_f32_e32 v234, v234
	v_mul_f32_e32 v229, v243, v229
	v_mul_f32_e32 v231, v243, v231
	v_mul_f32_e32 v233, v243, v233
	v_mul_f32_e32 v235, v243, v235
	v_add_f32_e32 v228, 1.0, v228
	v_add_f32_e32 v230, 1.0, v230
	v_add_f32_e32 v232, 1.0, v232
	v_add_f32_e32 v234, 1.0, v234
	v_rcp_f32_e32 v228, v228
	v_rcp_f32_e32 v230, v230
	v_rcp_f32_e32 v232, v232
	v_rcp_f32_e32 v234, v234
	v_mul_f32_e32 v68, v229, v228
	v_mul_f32_e32 v69, v231, v230
	v_mul_f32_e32 v70, v233, v232
	v_mul_f32_e32 v67, v235, v234
	s_nop 0
	v_cvt_pk_bf16_f32 v64, v76, v77
	v_cvt_pk_bf16_f32 v65, v78, v74
	v_cvt_pk_bf16_f32 v66, v68, v69
	v_cvt_pk_bf16_f32 v67, v70, v67
	global_store_dwordx4 v[112:113], v[64:67], off offset:3072
	s_nop 1
	v_or_b32_e32 v66, s9, v157
	v_lshlrev_b32_e32 v168, 6, v66
	s_nop 0
	v_mul_f32_e32 v244, 0xbfb8aa3b, v152
	v_mul_f32_e32 v245, v152, v152
	v_mul_f32_e32 v220, v244, v60
	v_mul_f32_e32 v222, v244, v61
	v_mul_f32_e32 v224, v244, v62
	v_mul_f32_e32 v226, v244, v63
	v_mul_f32_e32 v221, v60, v56
	v_mul_f32_e32 v223, v61, v57
	v_mul_f32_e32 v225, v62, v58
	v_mul_f32_e32 v227, v63, v59
	v_exp_f32_e32 v220, v220
	v_exp_f32_e32 v222, v222
	v_exp_f32_e32 v224, v224
	v_exp_f32_e32 v226, v226
	v_mul_f32_e32 v221, v245, v221
	v_mul_f32_e32 v223, v245, v223
	v_mul_f32_e32 v225, v245, v225
	v_mul_f32_e32 v227, v245, v227
	v_add_f32_e32 v220, 1.0, v220
	v_add_f32_e32 v222, 1.0, v222
	v_add_f32_e32 v224, 1.0, v224
	v_add_f32_e32 v226, 1.0, v226
	v_rcp_f32_e32 v220, v220
	v_rcp_f32_e32 v222, v222
	v_rcp_f32_e32 v224, v224
	v_rcp_f32_e32 v226, v226
	v_mul_f32_e32 v60, v221, v220
	v_mul_f32_e32 v61, v223, v222
	v_mul_f32_e32 v62, v225, v224
	v_mul_f32_e32 v58, v227, v226
	s_nop 0
	s_nop 0
	s_nop 0
	v_mul_f32_e32 v228, v244, v52
	v_mul_f32_e32 v230, v244, v53
	v_mul_f32_e32 v232, v244, v54
	v_mul_f32_e32 v234, v244, v55
	v_mul_f32_e32 v229, v52, v48
	v_mul_f32_e32 v231, v53, v49
	v_mul_f32_e32 v233, v54, v50
	v_mul_f32_e32 v235, v55, v51
	v_exp_f32_e32 v228, v228
	v_exp_f32_e32 v230, v230
	v_exp_f32_e32 v232, v232
	v_exp_f32_e32 v234, v234
	v_mul_f32_e32 v229, v245, v229
	v_mul_f32_e32 v231, v245, v231
	v_mul_f32_e32 v233, v245, v233
	v_mul_f32_e32 v235, v245, v235
	v_add_f32_e32 v228, 1.0, v228
	v_add_f32_e32 v230, 1.0, v230
	v_add_f32_e32 v232, 1.0, v232
	v_add_f32_e32 v234, 1.0, v234
	v_rcp_f32_e32 v228, v228
	v_rcp_f32_e32 v230, v230
	v_rcp_f32_e32 v232, v232
	v_rcp_f32_e32 v234, v234
	v_mul_f32_e32 v52, v229, v228
	v_mul_f32_e32 v53, v231, v230
	v_mul_f32_e32 v54, v233, v232
	v_mul_f32_e32 v48, v235, v234
	v_cvt_pk_bf16_f32 v50, v60, v61
	v_cvt_pk_bf16_f32 v51, v62, v58
	v_cvt_pk_bf16_f32 v52, v52, v53
	s_nop 0
	v_cvt_pk_bf16_f32 v53, v54, v48
	v_lshl_add_u64 v[48:49], s[0:1], 0, v[168:169]
	v_lshl_add_u64 v[48:49], v[48:49], 0, v[144:145]
	global_store_dwordx4 v[48:49], v[50:53], off
	s_mov_b64 s[0:1], -1
	s_nop 0
	s_nop 0
	s_nop 0
	v_mul_f32_e32 v246, 0xbfb8aa3b, v150
	v_mul_f32_e32 v247, v150, v150
	v_mul_f32_e32 v220, v246, v44
	v_mul_f32_e32 v222, v246, v45
	v_mul_f32_e32 v224, v246, v46
	v_mul_f32_e32 v226, v246, v47
	v_mul_f32_e32 v221, v44, v40
	v_mul_f32_e32 v223, v45, v41
	v_mul_f32_e32 v225, v46, v42
	v_mul_f32_e32 v227, v47, v43
	v_exp_f32_e32 v220, v220
	v_exp_f32_e32 v222, v222
	v_exp_f32_e32 v224, v224
	v_exp_f32_e32 v226, v226
	v_mul_f32_e32 v221, v247, v221
	v_mul_f32_e32 v223, v247, v223
	v_mul_f32_e32 v225, v247, v225
	v_mul_f32_e32 v227, v247, v227
	v_add_f32_e32 v220, 1.0, v220
	v_add_f32_e32 v222, 1.0, v222
	v_add_f32_e32 v224, 1.0, v224
	v_add_f32_e32 v226, 1.0, v226
	v_rcp_f32_e32 v220, v220
	v_rcp_f32_e32 v222, v222
	v_rcp_f32_e32 v224, v224
	v_rcp_f32_e32 v226, v226
	v_mul_f32_e32 v44, v221, v220
	v_mul_f32_e32 v45, v223, v222
	v_mul_f32_e32 v46, v225, v224
	v_mul_f32_e32 v42, v227, v226
	s_nop 0
	s_nop 0
	s_nop 0
	v_mul_f32_e32 v228, v246, v36
	v_mul_f32_e32 v230, v246, v37
	v_mul_f32_e32 v232, v246, v38
	v_mul_f32_e32 v234, v246, v39
	v_mul_f32_e32 v229, v36, v32
	v_mul_f32_e32 v231, v37, v33
	v_mul_f32_e32 v233, v38, v34
	v_mul_f32_e32 v235, v39, v35
	v_exp_f32_e32 v228, v228
	v_exp_f32_e32 v230, v230
	v_exp_f32_e32 v232, v232
	v_exp_f32_e32 v234, v234
	v_mul_f32_e32 v229, v247, v229
	v_mul_f32_e32 v231, v247, v231
	v_mul_f32_e32 v233, v247, v233
	v_mul_f32_e32 v235, v247, v235
	v_add_f32_e32 v228, 1.0, v228
	v_add_f32_e32 v230, 1.0, v230
	v_add_f32_e32 v232, 1.0, v232
	v_add_f32_e32 v234, 1.0, v234
	v_rcp_f32_e32 v228, v228
	v_rcp_f32_e32 v230, v230
	v_rcp_f32_e32 v232, v232
	v_rcp_f32_e32 v234, v234
	v_mul_f32_e32 v36, v229, v228
	v_mul_f32_e32 v37, v231, v230
	v_mul_f32_e32 v38, v233, v232
	v_mul_f32_e32 v35, v235, v234
	s_nop 0
	v_cvt_pk_bf16_f32 v32, v44, v45
	v_cvt_pk_bf16_f32 v33, v46, v42
	v_cvt_pk_bf16_f32 v34, v36, v37
	v_cvt_pk_bf16_f32 v35, v38, v35
	global_store_dwordx4 v[48:49], v[32:35], off offset:1024
	s_nop 1
	s_nop 0
	s_nop 0
	v_mul_f32_e32 v248, 0xbfb8aa3b, v148
	v_mul_f32_e32 v249, v148, v148
	v_mul_f32_e32 v220, v248, v28
	v_mul_f32_e32 v222, v248, v29
	v_mul_f32_e32 v224, v248, v30
	v_mul_f32_e32 v226, v248, v31
	v_mul_f32_e32 v221, v28, v24
	v_mul_f32_e32 v223, v29, v25
	v_mul_f32_e32 v225, v30, v26
	v_mul_f32_e32 v227, v31, v27
	v_exp_f32_e32 v220, v220
	v_exp_f32_e32 v222, v222
	v_exp_f32_e32 v224, v224
	v_exp_f32_e32 v226, v226
	v_mul_f32_e32 v221, v249, v221
	v_mul_f32_e32 v223, v249, v223
	v_mul_f32_e32 v225, v249, v225
	v_mul_f32_e32 v227, v249, v227
	v_add_f32_e32 v220, 1.0, v220
	v_add_f32_e32 v222, 1.0, v222
	v_add_f32_e32 v224, 1.0, v224
	v_add_f32_e32 v226, 1.0, v226
	v_rcp_f32_e32 v220, v220
	v_rcp_f32_e32 v222, v222
	v_rcp_f32_e32 v224, v224
	v_rcp_f32_e32 v226, v226
	v_mul_f32_e32 v28, v221, v220
	v_mul_f32_e32 v29, v223, v222
	v_mul_f32_e32 v30, v225, v224
	v_mul_f32_e32 v26, v227, v226
	s_nop 0
	s_nop 0
	s_nop 0
	v_mul_f32_e32 v228, v248, v20
	v_mul_f32_e32 v230, v248, v21
	v_mul_f32_e32 v232, v248, v22
	v_mul_f32_e32 v234, v248, v23
	v_mul_f32_e32 v229, v20, v16
	v_mul_f32_e32 v231, v21, v17
	v_mul_f32_e32 v233, v22, v18
	v_mul_f32_e32 v235, v23, v19
	v_exp_f32_e32 v228, v228
	v_exp_f32_e32 v230, v230
	v_exp_f32_e32 v232, v232
	v_exp_f32_e32 v234, v234
	v_mul_f32_e32 v229, v249, v229
	v_mul_f32_e32 v231, v249, v231
	v_mul_f32_e32 v233, v249, v233
	v_mul_f32_e32 v235, v249, v235
	v_add_f32_e32 v228, 1.0, v228
	v_add_f32_e32 v230, 1.0, v230
	v_add_f32_e32 v232, 1.0, v232
	v_add_f32_e32 v234, 1.0, v234
	v_rcp_f32_e32 v228, v228
	v_rcp_f32_e32 v230, v230
	v_rcp_f32_e32 v232, v232
	v_rcp_f32_e32 v234, v234
	v_mul_f32_e32 v20, v229, v228
	v_mul_f32_e32 v21, v231, v230
	v_mul_f32_e32 v22, v233, v232
	v_mul_f32_e32 v19, v235, v234
	s_nop 0
	v_cvt_pk_bf16_f32 v16, v28, v29
	v_cvt_pk_bf16_f32 v17, v30, v26
	v_cvt_pk_bf16_f32 v18, v20, v21
	v_cvt_pk_bf16_f32 v19, v22, v19
	global_store_dwordx4 v[48:49], v[16:19], off offset:2048
	s_nop 1
	s_nop 0
	s_nop 0
	v_mul_f32_e32 v250, 0xbfb8aa3b, v146
	v_mul_f32_e32 v251, v146, v146
	v_mul_f32_e32 v220, v250, v12
	v_mul_f32_e32 v222, v250, v13
	v_mul_f32_e32 v224, v250, v14
	v_mul_f32_e32 v226, v250, v15
	v_mul_f32_e32 v221, v12, v8
	v_mul_f32_e32 v223, v13, v9
	v_mul_f32_e32 v225, v14, v10
	v_mul_f32_e32 v227, v15, v11
	v_exp_f32_e32 v220, v220
	v_exp_f32_e32 v222, v222
	v_exp_f32_e32 v224, v224
	v_exp_f32_e32 v226, v226
	v_mul_f32_e32 v221, v251, v221
	v_mul_f32_e32 v223, v251, v223
	v_mul_f32_e32 v225, v251, v225
	v_mul_f32_e32 v227, v251, v227
	v_add_f32_e32 v220, 1.0, v220
	v_add_f32_e32 v222, 1.0, v222
	v_add_f32_e32 v224, 1.0, v224
	v_add_f32_e32 v226, 1.0, v226
	v_rcp_f32_e32 v220, v220
	v_rcp_f32_e32 v222, v222
	v_rcp_f32_e32 v224, v224
	v_rcp_f32_e32 v226, v226
	v_mul_f32_e32 v12, v221, v220
	v_mul_f32_e32 v13, v223, v222
	v_mul_f32_e32 v14, v225, v224
	v_mul_f32_e32 v10, v227, v226
	s_nop 0
	s_nop 0
	s_nop 0
	v_mul_f32_e32 v228, v250, v4
	v_mul_f32_e32 v230, v250, v5
	v_mul_f32_e32 v232, v250, v6
	v_mul_f32_e32 v234, v250, v7
	v_mul_f32_e32 v229, v4, v0
	v_mul_f32_e32 v231, v5, v1
	v_mul_f32_e32 v233, v6, v2
	v_mul_f32_e32 v235, v7, v3
	v_exp_f32_e32 v228, v228
	v_exp_f32_e32 v230, v230
	v_exp_f32_e32 v232, v232
	v_exp_f32_e32 v234, v234
	v_mul_f32_e32 v229, v251, v229
	v_mul_f32_e32 v231, v251, v231
	v_mul_f32_e32 v233, v251, v233
	v_mul_f32_e32 v235, v251, v235
	v_add_f32_e32 v228, 1.0, v228
	v_add_f32_e32 v230, 1.0, v230
	v_add_f32_e32 v232, 1.0, v232
	v_add_f32_e32 v234, 1.0, v234
	v_rcp_f32_e32 v228, v228
	v_rcp_f32_e32 v230, v230
	v_rcp_f32_e32 v232, v232
	v_rcp_f32_e32 v234, v234
	v_mul_f32_e32 v4, v229, v228
	v_mul_f32_e32 v5, v231, v230
	v_mul_f32_e32 v6, v233, v232
	v_mul_f32_e32 v3, v235, v234
	s_nop 0
	v_cvt_pk_bf16_f32 v0, v12, v13
	v_cvt_pk_bf16_f32 v1, v14, v10
	v_cvt_pk_bf16_f32 v2, v4, v5
	v_cvt_pk_bf16_f32 v3, v6, v3
	global_store_dwordx4 v[48:49], v[0:3], off offset:3072
	s_cbranch_vccnz .LBB0_1061
	s_andn2_b64 vcc, exec, s[4:5]
	s_cbranch_vccnz .LBB0_1060
	s_barrier
	s_branch .LBB0_1060

.LBB0_1144:
	v_lshl_add_u32 v166, s57, 8, v170
	v_lshl_or_b32 v158, s56, 8, v197
	v_ashrrev_i32_e32 v167, 31, v166
	v_lshlrev_b64 v[120:121], 11, v[166:167]
	v_ashrrev_i32_e32 v159, 31, v158
	v_lshl_add_u64 v[160:161], s[42:43], 0, v[120:121]
	v_lshlrev_b64 v[120:121], 1, v[158:159]
	v_lshl_add_u64 v[194:195], v[160:161], 0, v[120:121]
	global_load_dwordx4 v[178:181], v[194:195], off
	global_load_dwordx4 v[144:147], v[194:195], off offset:256
	v_or_b32_e32 v190, 16, v166
	v_ashrrev_i32_e32 v191, 31, v190
	v_lshlrev_b64 v[122:123], 11, v[190:191]
	v_or_b32_e32 v162, 32, v166
	v_lshl_add_u64 v[122:123], s[42:43], 0, v[122:123]
	v_ashrrev_i32_e32 v163, 31, v162
	v_lshl_add_u64 v[192:193], v[122:123], 0, v[120:121]
	v_lshlrev_b64 v[122:123], 11, v[162:163]
	v_lshl_add_u64 v[122:123], s[42:43], 0, v[122:123]
	v_lshl_add_u64 v[164:165], v[122:123], 0, v[120:121]
	global_load_dwordx4 v[140:143], v[192:193], off
	global_load_dwordx4 v[128:131], v[192:193], off offset:256
	global_load_dwordx4 v[124:127], v[164:165], off
	global_load_dwordx4 v[120:123], v[164:165], off offset:256
	s_lshl_b32 s12, s56, 2
	s_ashr_i32 s13, s12, 31
	s_waitcnt vmcnt(0)
	v_lshlrev_b32_e32 v199, 16, v178
	v_and_b32_e32 v178, 0xffff0000, v178
	v_add_f32_e32 v178, 0, v178
	v_add_f32_e32 v137, v137, v178
	v_lshlrev_b32_e32 v178, 16, v179
	v_and_b32_e32 v179, 0xffff0000, v179
	v_add_f32_e32 v178, 0, v178
	v_add_f32_e32 v179, 0, v179
	v_add_f32_e32 v138, v138, v178
	v_add_f32_e32 v139, v139, v179
	v_lshlrev_b32_e32 v178, 16, v180
	v_and_b32_e32 v179, 0xffff0000, v180
	v_add_f32_e32 v178, 0, v178
	v_add_f32_e32 v179, 0, v179
	v_add_f32_e32 v178, v132, v178
	v_add_f32_e32 v179, v133, v179
	v_lshlrev_b32_e32 v132, 16, v181
	v_and_b32_e32 v133, 0xffff0000, v181
	v_add_f32_e32 v199, 0, v199
	v_add_f32_e32 v132, 0, v132
	v_add_f32_e32 v133, 0, v133
	v_add_f32_e32 v136, v136, v199
	v_add_f32_e32 v180, v134, v132
	v_add_f32_e32 v181, v135, v133
	v_cvt_pk_bf16_f32 v132, v136, v137
	s_nop 0
	v_mul_f32_e32 v134, v137, v137
	v_cvt_pk_bf16_f32 v133, v138, v139
	v_fmac_f32_e32 v134, v136, v136
	s_nop 0
	v_mul_f32_e32 v135, v139, v139
	v_fmac_f32_e32 v135, v138, v138
	v_add_f32_e32 v135, v134, v135
	v_cvt_pk_bf16_f32 v134, v178, v179
	s_nop 0
	s_nop 0
	v_mul_f32_e32 v136, v179, v179
	v_fmac_f32_e32 v136, v178, v178
	v_add_f32_e32 v136, v136, v135
	v_cvt_pk_bf16_f32 v135, v180, v181
	s_nop 0
	global_store_dwordx4 v[194:195], v[132:135], off
	v_mul_f32_e32 v137, v181, v181
	v_fmac_f32_e32 v137, v180, v180
	v_lshlrev_b32_e32 v132, 16, v144
	v_and_b32_e32 v133, 0xffff0000, v144
	v_add_f32_e32 v132, 0, v132
	v_add_f32_e32 v133, 0, v133
	v_add_f32_e32 v116, v116, v132
	v_add_f32_e32 v117, v117, v133
	v_lshlrev_b32_e32 v132, 16, v145
	v_and_b32_e32 v133, 0xffff0000, v145
	v_add_f32_e32 v132, 0, v132
	v_add_f32_e32 v133, 0, v133
	v_add_f32_e32 v118, v118, v132
	v_add_f32_e32 v119, v119, v133
	v_lshlrev_b32_e32 v132, 16, v146
	v_and_b32_e32 v133, 0xffff0000, v146
	v_add_f32_e32 v132, 0, v132
	v_add_f32_e32 v133, 0, v133
	v_add_f32_e32 v132, v112, v132
	v_add_f32_e32 v133, v113, v133
	v_lshlrev_b32_e32 v112, 16, v147
	v_and_b32_e32 v113, 0xffff0000, v147
	v_add_f32_e32 v112, 0, v112
	v_add_f32_e32 v113, 0, v113
	v_add_f32_e32 v134, v114, v112
	v_add_f32_e32 v135, v115, v113
	v_cvt_pk_bf16_f32 v112, v116, v117
	v_add_f32_e32 v136, v137, v136
	s_nop 0
	v_mul_f32_e32 v113, v117, v117
	v_fmac_f32_e32 v113, v116, v116
	v_add_f32_e32 v114, v113, v136
	v_cvt_pk_bf16_f32 v113, v118, v119
	s_nop 0
	s_nop 0
	v_mul_f32_e32 v115, v119, v119
	v_fmac_f32_e32 v115, v118, v118
	v_add_f32_e32 v115, v115, v114
	v_cvt_pk_bf16_f32 v114, v132, v133
	s_nop 0
	s_nop 0
	v_mul_f32_e32 v116, v133, v133
	v_fmac_f32_e32 v116, v132, v132
	v_add_f32_e32 v116, v116, v115
	v_cvt_pk_bf16_f32 v115, v134, v135
	s_nop 0
	global_store_dwordx4 v[194:195], v[112:115], off offset:256
	v_mul_f32_e32 v117, v135, v135
	v_fmac_f32_e32 v117, v134, v134
	v_and_b32_e32 v113, 64, v213
	v_xor_b32_e32 v112, 16, v213
	v_add_u32_e32 v113, 64, v113
	v_cmp_lt_i32_e32 vcc, v112, v113
	v_add_f32_e32 v116, v117, v116
	v_xor_b32_e32 v114, 32, v213
	v_cndmask_b32_e32 v112, v213, v112, vcc
	v_lshlrev_b32_e32 v136, 2, v112
	ds_bpermute_b32 v112, v136, v116
	v_cmp_lt_i32_e32 vcc, v114, v113
	s_waitcnt lgkmcnt(0)
	v_add_f32_e32 v112, v116, v112
	v_cndmask_b32_e32 v113, v213, v114, vcc
	v_lshlrev_b32_e32 v137, 2, v113
	ds_bpermute_b32 v113, v137, v112
	s_and_saveexec_b64 s[14:15], s[2:3]
	s_cbranch_execz .LBB0_1146
	s_waitcnt lgkmcnt(0)
	v_add_f32_e32 v114, v112, v113
	v_lshlrev_b64 v[112:113], 6, v[166:167]
	v_lshl_add_u64 v[112:113], s[40:41], 0, v[112:113]
	v_lshl_add_u64 v[112:113], s[12:13], 2, v[112:113]
	s_lshl_b32 s90, s35, 2
	v_lshl_add_u64 v[112:113], v[112:113], 0, s[90:91]
	global_store_dword v[112:113], v114, off
.LBB0_1146:
	s_or_b64 exec, exec, s[14:15]
	v_or_b32_e32 v132, 48, v166
	v_ashrrev_i32_e32 v133, 31, v132
	s_waitcnt lgkmcnt(0)
	v_lshlrev_b64 v[112:113], 11, v[132:133]
	v_lshl_add_u64 v[112:113], s[42:43], 0, v[112:113]
	v_lshl_add_u64 v[134:135], v[158:159], 1, v[112:113]
	global_load_dwordx4 v[116:119], v[134:135], off
	global_load_dwordx4 v[112:115], v[134:135], off offset:256
	v_lshlrev_b32_e32 v138, 16, v140
	v_and_b32_e32 v139, 0xffff0000, v140
	v_add_f32_e32 v138, 0, v138
	v_add_f32_e32 v139, 0, v139
	v_add_f32_e32 v108, v108, v138
	v_add_f32_e32 v109, v109, v139
	v_lshlrev_b32_e32 v138, 16, v141
	v_and_b32_e32 v139, 0xffff0000, v141
	v_add_f32_e32 v138, 0, v138
	v_add_f32_e32 v139, 0, v139
	v_add_f32_e32 v110, v110, v138
	v_add_f32_e32 v111, v111, v139
	v_lshlrev_b32_e32 v138, 16, v142
	v_and_b32_e32 v139, 0xffff0000, v142
	v_add_f32_e32 v138, 0, v138
	v_add_f32_e32 v139, 0, v139
	v_add_f32_e32 v138, v104, v138
	v_add_f32_e32 v139, v105, v139
	v_lshlrev_b32_e32 v104, 16, v143
	v_and_b32_e32 v105, 0xffff0000, v143
	v_add_f32_e32 v104, 0, v104
	v_add_f32_e32 v105, 0, v105
	v_add_f32_e32 v140, v106, v104
	v_add_f32_e32 v141, v107, v105
	v_cvt_pk_bf16_f32 v104, v108, v109
	s_nop 0
	v_mul_f32_e32 v106, v109, v109
	v_cvt_pk_bf16_f32 v105, v110, v111
	v_fmac_f32_e32 v106, v108, v108
	s_nop 0
	v_mul_f32_e32 v107, v111, v111
	v_fmac_f32_e32 v107, v110, v110
	v_add_f32_e32 v107, v106, v107
	v_cvt_pk_bf16_f32 v106, v138, v139
	s_nop 0
	s_nop 0
	v_mul_f32_e32 v108, v139, v139
	v_fmac_f32_e32 v108, v138, v138
	v_add_f32_e32 v108, v108, v107
	v_cvt_pk_bf16_f32 v107, v140, v141
	s_nop 0
	global_store_dwordx4 v[192:193], v[104:107], off
	v_mul_f32_e32 v109, v141, v141
	v_fmac_f32_e32 v109, v140, v140
	v_lshlrev_b32_e32 v104, 16, v128
	v_and_b32_e32 v105, 0xffff0000, v128
	v_add_f32_e32 v104, 0, v104
	v_add_f32_e32 v105, 0, v105
	v_add_f32_e32 v100, v100, v104
	v_add_f32_e32 v101, v101, v105
	v_lshlrev_b32_e32 v104, 16, v129
	v_and_b32_e32 v105, 0xffff0000, v129
	v_add_f32_e32 v104, 0, v104
	v_add_f32_e32 v105, 0, v105
	v_add_f32_e32 v102, v102, v104
	v_add_f32_e32 v103, v103, v105
	v_lshlrev_b32_e32 v104, 16, v130
	v_and_b32_e32 v105, 0xffff0000, v130
	v_add_f32_e32 v104, 0, v104
	v_add_f32_e32 v105, 0, v105
	v_add_f32_e32 v96, v96, v104
	v_add_f32_e32 v97, v97, v105
	v_lshlrev_b32_e32 v104, 16, v131
	v_and_b32_e32 v105, 0xffff0000, v131
	v_add_f32_e32 v104, 0, v104
	v_add_f32_e32 v105, 0, v105
	v_add_f32_e32 v104, v98, v104
	v_add_f32_e32 v105, v99, v105
	v_cvt_pk_bf16_f32 v98, v100, v101
	v_add_f32_e32 v108, v109, v108
	s_nop 0
	v_mul_f32_e32 v99, v101, v101
	v_fmac_f32_e32 v99, v100, v100
	v_add_f32_e32 v100, v99, v108
	v_cvt_pk_bf16_f32 v99, v102, v103
	s_nop 0
	s_nop 0
	v_mul_f32_e32 v101, v103, v103
	v_fmac_f32_e32 v101, v102, v102
	v_add_f32_e32 v101, v101, v100
	v_cvt_pk_bf16_f32 v100, v96, v97
	s_nop 0
	v_mul_f32_e32 v97, v97, v97
	v_fmac_f32_e32 v97, v96, v96
	v_add_f32_e32 v96, v97, v101
	v_mul_f32_e32 v97, v105, v105
	v_fmac_f32_e32 v97, v104, v104
	v_add_f32_e32 v96, v97, v96
	ds_bpermute_b32 v97, v136, v96
	s_waitcnt lgkmcnt(0)
	v_add_f32_e32 v96, v96, v97
	ds_bpermute_b32 v97, v137, v96
	v_cvt_pk_bf16_f32 v101, v104, v105
	s_nop 0
	global_store_dwordx4 v[192:193], v[98:101], off offset:256
	s_and_saveexec_b64 s[14:15], s[2:3]
	s_cbranch_execz .LBB0_1148
	s_waitcnt lgkmcnt(0)
	v_add_f32_e32 v98, v96, v97
	v_lshlrev_b64 v[96:97], 6, v[190:191]
	v_lshl_add_u64 v[96:97], s[40:41], 0, v[96:97]
	v_lshl_add_u64 v[96:97], s[12:13], 2, v[96:97]
	s_lshl_b32 s90, s35, 2
	v_lshl_add_u64 v[96:97], v[96:97], 0, s[90:91]
	global_store_dword v[96:97], v98, off
.LBB0_1148:
	s_or_b64 exec, exec, s[14:15]
	v_add_u32_e32 v104, 0x80, v166
	v_ashrrev_i32_e32 v105, 31, v104
	s_waitcnt lgkmcnt(0)
	v_lshlrev_b64 v[96:97], 11, v[104:105]
	v_lshl_add_u64 v[96:97], s[42:43], 0, v[96:97]
	v_lshl_add_u64 v[106:107], v[158:159], 1, v[96:97]
	global_load_dwordx4 v[100:103], v[106:107], off
	global_load_dwordx4 v[96:99], v[106:107], off offset:256
	v_lshlrev_b32_e32 v108, 16, v124
	v_and_b32_e32 v109, 0xffff0000, v124
	v_add_f32_e32 v108, 0, v108
	v_add_f32_e32 v109, 0, v109
	v_add_f32_e32 v92, v92, v108
	v_add_f32_e32 v93, v93, v109
	v_lshlrev_b32_e32 v108, 16, v125
	v_and_b32_e32 v109, 0xffff0000, v125
	v_add_f32_e32 v108, 0, v108
	v_add_f32_e32 v109, 0, v109
	v_add_f32_e32 v94, v94, v108
	v_add_f32_e32 v95, v95, v109
	v_lshlrev_b32_e32 v108, 16, v126
	v_and_b32_e32 v109, 0xffff0000, v126
	v_add_f32_e32 v108, 0, v108
	v_add_f32_e32 v109, 0, v109
	v_add_f32_e32 v108, v88, v108
	v_add_f32_e32 v109, v89, v109
	v_lshlrev_b32_e32 v88, 16, v127
	v_and_b32_e32 v89, 0xffff0000, v127
	v_add_f32_e32 v88, 0, v88
	v_add_f32_e32 v89, 0, v89
	v_add_f32_e32 v110, v90, v88
	v_add_f32_e32 v111, v91, v89
	v_cvt_pk_bf16_f32 v88, v92, v93
	s_nop 0
	v_mul_f32_e32 v90, v93, v93
	v_cvt_pk_bf16_f32 v89, v94, v95
	v_fmac_f32_e32 v90, v92, v92
	s_nop 0
	v_mul_f32_e32 v91, v95, v95
	v_fmac_f32_e32 v91, v94, v94
	v_add_f32_e32 v91, v90, v91
	v_cvt_pk_bf16_f32 v90, v108, v109
	s_nop 0
	s_nop 0
	v_mul_f32_e32 v92, v109, v109
	v_fmac_f32_e32 v92, v108, v108
	v_add_f32_e32 v92, v92, v91
	v_cvt_pk_bf16_f32 v91, v110, v111
	s_nop 0
	v_and_b32_e32 v94, 0xffff0000, v91
	v_sub_f32_e32 v94, v111, v94
	global_store_dwordx4 v[164:165], v[88:91], off
	v_mul_f32_e32 v93, v111, v111
	v_fmac_f32_e32 v93, v110, v110
	v_lshlrev_b32_e32 v88, 16, v120
	v_and_b32_e32 v89, 0xffff0000, v120
	v_add_f32_e32 v88, 0, v88
	v_add_f32_e32 v89, 0, v89
	v_add_f32_e32 v84, v84, v88
	v_add_f32_e32 v85, v85, v89
	v_lshlrev_b32_e32 v88, 16, v121
	v_and_b32_e32 v89, 0xffff0000, v121
	v_add_f32_e32 v88, 0, v88
	v_add_f32_e32 v89, 0, v89
	v_add_f32_e32 v86, v86, v88
	v_add_f32_e32 v87, v87, v89
	v_lshlrev_b32_e32 v88, 16, v122
	v_and_b32_e32 v89, 0xffff0000, v122
	v_add_f32_e32 v88, 0, v88
	v_add_f32_e32 v89, 0, v89
	v_add_f32_e32 v80, v80, v88
	v_add_f32_e32 v81, v81, v89
	v_lshlrev_b32_e32 v88, 16, v123
	v_and_b32_e32 v89, 0xffff0000, v123
	v_add_f32_e32 v88, 0, v88
	v_add_f32_e32 v89, 0, v89
	v_add_f32_e32 v88, v82, v88
	v_add_f32_e32 v89, v83, v89
	v_cvt_pk_bf16_f32 v82, v84, v85
	v_add_f32_e32 v92, v93, v92
	s_nop 0
	v_mul_f32_e32 v83, v85, v85
	v_fmac_f32_e32 v83, v84, v84
	v_add_f32_e32 v84, v83, v92
	v_cvt_pk_bf16_f32 v83, v86, v87
	s_nop 0
	s_nop 0
	v_mul_f32_e32 v85, v87, v87
	v_fmac_f32_e32 v85, v86, v86
	v_add_f32_e32 v85, v85, v84
	v_cvt_pk_bf16_f32 v84, v80, v81
	s_nop 0
	v_mul_f32_e32 v81, v81, v81
	v_fmac_f32_e32 v81, v80, v80
	v_add_f32_e32 v80, v81, v85
	v_mul_f32_e32 v81, v89, v89
	v_fmac_f32_e32 v81, v88, v88
	v_add_f32_e32 v80, v81, v80
	ds_bpermute_b32 v81, v136, v80
	s_waitcnt lgkmcnt(0)
	v_add_f32_e32 v80, v80, v81
	ds_bpermute_b32 v81, v137, v80
	v_cvt_pk_bf16_f32 v85, v88, v89
	s_nop 0
	global_store_dwordx4 v[164:165], v[82:85], off offset:256
	s_and_saveexec_b64 s[14:15], s[2:3]
	s_cbranch_execz .LBB0_1150
	s_waitcnt lgkmcnt(0)
	v_add_f32_e32 v82, v80, v81
	v_lshlrev_b64 v[80:81], 6, v[162:163]
	v_lshl_add_u64 v[80:81], s[40:41], 0, v[80:81]
	v_lshl_add_u64 v[80:81], s[12:13], 2, v[80:81]
	s_lshl_b32 s90, s35, 2
	v_lshl_add_u64 v[80:81], v[80:81], 0, s[90:91]
	global_store_dword v[80:81], v82, off
.LBB0_1150:
	s_or_b64 exec, exec, s[14:15]
	s_waitcnt lgkmcnt(0)
	v_lshl_add_u64 v[80:81], v[158:159], 1, v[160:161]
	s_mov_b64 s[14:15], 0x48000
	v_lshl_add_u64 v[88:89], v[80:81], 0, s[14:15]
	v_add_co_u32_e32 v80, vcc, 0x48000, v80
	s_waitcnt vmcnt(7)
	v_lshlrev_b32_e32 v90, 16, v116
	v_addc_co_u32_e32 v81, vcc, 0, v81, vcc
	global_load_dwordx4 v[84:87], v[80:81], off
	s_nop 0
	global_load_dwordx4 v[80:83], v[88:89], off offset:256
	v_and_b32_e32 v91, 0xffff0000, v116
	v_add_f32_e32 v90, 0, v90
	v_add_f32_e32 v91, 0, v91
	v_add_f32_e32 v76, v76, v90
	v_add_f32_e32 v77, v77, v91
	v_lshlrev_b32_e32 v90, 16, v117
	v_and_b32_e32 v91, 0xffff0000, v117
	v_add_f32_e32 v90, 0, v90
	v_add_f32_e32 v91, 0, v91
	v_add_f32_e32 v78, v78, v90
	v_add_f32_e32 v79, v79, v91
	v_lshlrev_b32_e32 v90, 16, v118
	v_and_b32_e32 v91, 0xffff0000, v118
	v_add_f32_e32 v90, 0, v90
	v_add_f32_e32 v91, 0, v91
	v_add_f32_e32 v90, v72, v90
	v_add_f32_e32 v91, v73, v91
	v_lshlrev_b32_e32 v72, 16, v119
	v_and_b32_e32 v73, 0xffff0000, v119
	v_add_f32_e32 v72, 0, v72
	v_add_f32_e32 v73, 0, v73
	v_add_f32_e32 v92, v74, v72
	v_add_f32_e32 v93, v75, v73
	v_cvt_pk_bf16_f32 v72, v76, v77
	s_nop 0
	v_mul_f32_e32 v74, v77, v77
	v_cvt_pk_bf16_f32 v73, v78, v79
	v_fmac_f32_e32 v74, v76, v76
	s_nop 0
	v_mul_f32_e32 v75, v79, v79
	v_fmac_f32_e32 v75, v78, v78
	v_add_f32_e32 v75, v74, v75
	v_cvt_pk_bf16_f32 v74, v90, v91
	s_nop 0
	s_nop 0
	v_mul_f32_e32 v76, v91, v91
	v_fmac_f32_e32 v76, v90, v90
	v_add_f32_e32 v76, v76, v75
	v_cvt_pk_bf16_f32 v75, v92, v93
	s_nop 0
	global_store_dwordx4 v[134:135], v[72:75], off
	v_mul_f32_e32 v77, v93, v93
	v_fmac_f32_e32 v77, v92, v92
	s_waitcnt vmcnt(9)
	v_lshlrev_b32_e32 v72, 16, v112
	v_and_b32_e32 v73, 0xffff0000, v112
	v_add_f32_e32 v72, 0, v72
	v_add_f32_e32 v73, 0, v73
	v_add_f32_e32 v68, v68, v72
	v_add_f32_e32 v69, v69, v73
	v_lshlrev_b32_e32 v72, 16, v113
	v_and_b32_e32 v73, 0xffff0000, v113
	v_add_f32_e32 v72, 0, v72
	v_add_f32_e32 v73, 0, v73
	v_add_f32_e32 v70, v70, v72
	v_add_f32_e32 v71, v71, v73
	v_lshlrev_b32_e32 v72, 16, v114
	v_and_b32_e32 v73, 0xffff0000, v114
	v_add_f32_e32 v72, 0, v72
	v_add_f32_e32 v73, 0, v73
	v_add_f32_e32 v64, v64, v72
	v_add_f32_e32 v65, v65, v73
	v_lshlrev_b32_e32 v72, 16, v115
	v_and_b32_e32 v73, 0xffff0000, v115
	v_add_f32_e32 v72, 0, v72
	v_add_f32_e32 v73, 0, v73
	v_add_f32_e32 v72, v66, v72
	v_add_f32_e32 v73, v67, v73
	v_cvt_pk_bf16_f32 v66, v68, v69
	v_add_f32_e32 v76, v77, v76
	s_nop 0
	v_mul_f32_e32 v67, v69, v69
	v_fmac_f32_e32 v67, v68, v68
	v_add_f32_e32 v68, v67, v76
	v_cvt_pk_bf16_f32 v67, v70, v71
	s_nop 0
	s_nop 0
	v_mul_f32_e32 v69, v71, v71
	v_fmac_f32_e32 v69, v70, v70
	v_add_f32_e32 v69, v69, v68
	v_cvt_pk_bf16_f32 v68, v64, v65
	s_nop 0
	v_mul_f32_e32 v65, v65, v65
	v_fmac_f32_e32 v65, v64, v64
	v_add_f32_e32 v64, v65, v69
	v_mul_f32_e32 v65, v73, v73
	v_fmac_f32_e32 v65, v72, v72
	v_add_f32_e32 v64, v65, v64
	ds_bpermute_b32 v65, v136, v64
	s_waitcnt lgkmcnt(0)
	v_add_f32_e32 v64, v64, v65
	ds_bpermute_b32 v65, v137, v64
	v_cvt_pk_bf16_f32 v69, v72, v73
	s_nop 0
	global_store_dwordx4 v[134:135], v[66:69], off offset:256
	s_and_saveexec_b64 s[14:15], s[2:3]
	s_cbranch_execz .LBB0_1152
	s_waitcnt lgkmcnt(0)
	v_add_f32_e32 v66, v64, v65
	v_lshlrev_b64 v[64:65], 6, v[132:133]
	v_lshl_add_u64 v[64:65], s[40:41], 0, v[64:65]
	v_lshl_add_u64 v[64:65], s[12:13], 2, v[64:65]
	s_lshl_b32 s90, s35, 2
	v_lshl_add_u64 v[64:65], v[64:65], 0, s[90:91]
	global_store_dword v[64:65], v66, off
.LBB0_1152:
	s_or_b64 exec, exec, s[14:15]
	v_or_b32_e32 v72, 32, v104
	v_ashrrev_i32_e32 v73, 31, v72
	s_waitcnt lgkmcnt(0)
	v_lshlrev_b64 v[64:65], 11, v[72:73]
	v_lshl_add_u64 v[64:65], s[42:43], 0, v[64:65]
	v_lshl_add_u64 v[74:75], v[158:159], 1, v[64:65]
	global_load_dwordx4 v[68:71], v[74:75], off
	global_load_dwordx4 v[64:67], v[74:75], off offset:256
	s_waitcnt vmcnt(9)
	v_lshlrev_b32_e32 v76, 16, v100
	v_and_b32_e32 v77, 0xffff0000, v100
	v_add_f32_e32 v76, 0, v76
	v_add_f32_e32 v77, 0, v77
	v_add_f32_e32 v60, v60, v76
	v_add_f32_e32 v61, v61, v77
	v_lshlrev_b32_e32 v76, 16, v101
	v_and_b32_e32 v77, 0xffff0000, v101
	v_add_f32_e32 v76, 0, v76
	v_add_f32_e32 v77, 0, v77
	v_add_f32_e32 v62, v62, v76
	v_add_f32_e32 v63, v63, v77
	v_lshlrev_b32_e32 v76, 16, v102
	v_and_b32_e32 v77, 0xffff0000, v102
	v_add_f32_e32 v76, 0, v76
	v_add_f32_e32 v77, 0, v77
	v_add_f32_e32 v76, v56, v76
	v_add_f32_e32 v77, v57, v77
	v_lshlrev_b32_e32 v56, 16, v103
	v_and_b32_e32 v57, 0xffff0000, v103
	v_add_f32_e32 v56, 0, v56
	v_add_f32_e32 v57, 0, v57
	v_add_f32_e32 v78, v58, v56
	v_add_f32_e32 v79, v59, v57
	v_cvt_pk_bf16_f32 v56, v60, v61
	s_nop 0
	v_mul_f32_e32 v58, v61, v61
	v_cvt_pk_bf16_f32 v57, v62, v63
	v_fmac_f32_e32 v58, v60, v60
	s_nop 0
	v_mul_f32_e32 v59, v63, v63
	v_fmac_f32_e32 v59, v62, v62
	v_add_f32_e32 v59, v58, v59
	v_cvt_pk_bf16_f32 v58, v76, v77
	s_nop 0
	s_nop 0
	v_mul_f32_e32 v60, v77, v77
	v_fmac_f32_e32 v60, v76, v76
	v_add_f32_e32 v60, v60, v59
	v_cvt_pk_bf16_f32 v59, v78, v79
	s_nop 0
	global_store_dwordx4 v[106:107], v[56:59], off
	v_mul_f32_e32 v61, v79, v79
	v_fmac_f32_e32 v61, v78, v78
	s_waitcnt vmcnt(9)
	v_lshlrev_b32_e32 v56, 16, v96
	v_and_b32_e32 v57, 0xffff0000, v96
	v_add_f32_e32 v56, 0, v56
	v_add_f32_e32 v57, 0, v57
	v_add_f32_e32 v52, v52, v56
	v_add_f32_e32 v53, v53, v57
	v_lshlrev_b32_e32 v56, 16, v97
	v_and_b32_e32 v57, 0xffff0000, v97
	v_add_f32_e32 v56, 0, v56
	v_add_f32_e32 v57, 0, v57
	v_add_f32_e32 v54, v54, v56
	v_add_f32_e32 v55, v55, v57
	v_lshlrev_b32_e32 v56, 16, v98
	v_and_b32_e32 v57, 0xffff0000, v98
	v_add_f32_e32 v56, 0, v56
	v_add_f32_e32 v57, 0, v57
	v_add_f32_e32 v48, v48, v56
	v_add_f32_e32 v49, v49, v57
	v_lshlrev_b32_e32 v56, 16, v99
	v_and_b32_e32 v57, 0xffff0000, v99
	v_add_f32_e32 v56, 0, v56
	v_add_f32_e32 v57, 0, v57
	v_add_f32_e32 v56, v50, v56
	v_add_f32_e32 v57, v51, v57
	v_cvt_pk_bf16_f32 v50, v52, v53
	v_add_f32_e32 v60, v61, v60
	s_nop 0
	v_mul_f32_e32 v51, v53, v53
	v_fmac_f32_e32 v51, v52, v52
	v_add_f32_e32 v52, v51, v60
	v_cvt_pk_bf16_f32 v51, v54, v55
	s_nop 0
	s_nop 0
	v_mul_f32_e32 v53, v55, v55
	v_fmac_f32_e32 v53, v54, v54
	v_add_f32_e32 v53, v53, v52
	v_cvt_pk_bf16_f32 v52, v48, v49
	s_nop 0
	v_mul_f32_e32 v49, v49, v49
	v_fmac_f32_e32 v49, v48, v48
	v_add_f32_e32 v48, v49, v53
	v_mul_f32_e32 v49, v57, v57
	v_fmac_f32_e32 v49, v56, v56
	v_add_f32_e32 v48, v49, v48
	ds_bpermute_b32 v49, v136, v48
	s_waitcnt lgkmcnt(0)
	v_add_f32_e32 v48, v48, v49
	ds_bpermute_b32 v49, v137, v48
	v_cvt_pk_bf16_f32 v53, v56, v57
	s_nop 0
	global_store_dwordx4 v[106:107], v[50:53], off offset:256
	s_and_saveexec_b64 s[14:15], s[2:3]
	s_cbranch_execz .LBB0_1154
	s_waitcnt lgkmcnt(0)
	v_add_f32_e32 v50, v48, v49
	v_lshlrev_b64 v[48:49], 6, v[104:105]
	v_lshl_add_u64 v[48:49], s[40:41], 0, v[48:49]
	v_lshl_add_u64 v[48:49], s[12:13], 2, v[48:49]
	s_lshl_b32 s90, s35, 2
	v_lshl_add_u64 v[48:49], v[48:49], 0, s[90:91]
	global_store_dword v[48:49], v50, off
.LBB0_1154:
	s_or_b64 exec, exec, s[14:15]
	v_or_b32_e32 v56, 48, v104
	v_ashrrev_i32_e32 v57, 31, v56
	s_waitcnt lgkmcnt(0)
	v_lshlrev_b64 v[48:49], 11, v[56:57]
	v_lshl_add_u64 v[48:49], s[42:43], 0, v[48:49]
	v_lshl_add_u64 v[58:59], v[158:159], 1, v[48:49]
	global_load_dwordx4 v[52:55], v[58:59], off
	global_load_dwordx4 v[48:51], v[58:59], off offset:256
	s_waitcnt vmcnt(9)
	v_lshlrev_b32_e32 v60, 16, v84
	v_and_b32_e32 v61, 0xffff0000, v84
	v_add_f32_e32 v60, 0, v60
	v_add_f32_e32 v61, 0, v61
	v_add_f32_e32 v44, v44, v60
	v_add_f32_e32 v45, v45, v61
	v_lshlrev_b32_e32 v60, 16, v85
	v_and_b32_e32 v61, 0xffff0000, v85
	v_add_f32_e32 v60, 0, v60
	v_add_f32_e32 v61, 0, v61
	v_add_f32_e32 v46, v46, v60
	v_add_f32_e32 v47, v47, v61
	v_lshlrev_b32_e32 v60, 16, v86
	v_and_b32_e32 v61, 0xffff0000, v86
	v_add_f32_e32 v60, 0, v60
	v_add_f32_e32 v61, 0, v61
	v_add_f32_e32 v60, v40, v60
	v_add_f32_e32 v61, v41, v61
	v_lshlrev_b32_e32 v40, 16, v87
	v_and_b32_e32 v41, 0xffff0000, v87
	v_add_f32_e32 v40, 0, v40
	v_add_f32_e32 v41, 0, v41
	v_add_f32_e32 v62, v42, v40
	v_add_f32_e32 v63, v43, v41
	v_cvt_pk_bf16_f32 v40, v44, v45
	s_nop 0
	v_mul_f32_e32 v42, v45, v45
	v_cvt_pk_bf16_f32 v41, v46, v47
	v_fmac_f32_e32 v42, v44, v44
	s_nop 0
	v_mul_f32_e32 v43, v47, v47
	v_fmac_f32_e32 v43, v46, v46
	v_add_f32_e32 v43, v42, v43
	v_cvt_pk_bf16_f32 v42, v60, v61
	s_nop 0
	s_nop 0
	v_mul_f32_e32 v44, v61, v61
	v_fmac_f32_e32 v44, v60, v60
	v_add_f32_e32 v44, v44, v43
	v_cvt_pk_bf16_f32 v43, v62, v63
	s_nop 0
	v_and_b32_e32 v46, 0xffff0000, v43
	v_sub_f32_e32 v46, v63, v46
	global_store_dwordx4 v[88:89], v[40:43], off
	v_mul_f32_e32 v45, v63, v63
	v_fmac_f32_e32 v45, v62, v62
	s_waitcnt vmcnt(9)
	v_lshlrev_b32_e32 v40, 16, v80
	v_and_b32_e32 v41, 0xffff0000, v80
	v_add_f32_e32 v40, 0, v40
	v_add_f32_e32 v41, 0, v41
	v_add_f32_e32 v36, v36, v40
	v_add_f32_e32 v37, v37, v41
	v_lshlrev_b32_e32 v40, 16, v81
	v_and_b32_e32 v41, 0xffff0000, v81
	v_add_f32_e32 v40, 0, v40
	v_add_f32_e32 v41, 0, v41
	v_add_f32_e32 v38, v38, v40
	v_add_f32_e32 v39, v39, v41
	v_lshlrev_b32_e32 v40, 16, v82
	v_and_b32_e32 v41, 0xffff0000, v82
	v_add_f32_e32 v40, 0, v40
	v_add_f32_e32 v41, 0, v41
	v_add_f32_e32 v32, v32, v40
	v_add_f32_e32 v33, v33, v41
	v_lshlrev_b32_e32 v40, 16, v83
	v_and_b32_e32 v41, 0xffff0000, v83
	v_add_f32_e32 v40, 0, v40
	v_add_f32_e32 v41, 0, v41
	v_add_f32_e32 v40, v34, v40
	v_add_f32_e32 v41, v35, v41
	v_cvt_pk_bf16_f32 v34, v36, v37
	v_add_f32_e32 v44, v45, v44
	s_nop 0
	v_mul_f32_e32 v35, v37, v37
	v_fmac_f32_e32 v35, v36, v36
	v_add_f32_e32 v36, v35, v44
	v_cvt_pk_bf16_f32 v35, v38, v39
	s_nop 0
	v_and_b32_e32 v42, 0xffff0000, v35
	v_sub_f32_e32 v42, v39, v42
	s_nop 0
	v_mul_f32_e32 v37, v39, v39
	v_fmac_f32_e32 v37, v38, v38
	v_add_f32_e32 v37, v37, v36
	v_cvt_pk_bf16_f32 v36, v32, v33
	s_nop 0
	v_mul_f32_e32 v33, v33, v33
	v_fmac_f32_e32 v33, v32, v32
	v_add_f32_e32 v32, v33, v37
	v_mul_f32_e32 v33, v41, v41
	v_fmac_f32_e32 v33, v40, v40
	v_add_f32_e32 v32, v33, v32
	ds_bpermute_b32 v33, v136, v32
	s_waitcnt lgkmcnt(0)
	v_add_f32_e32 v32, v32, v33
	ds_bpermute_b32 v33, v137, v32
	v_cvt_pk_bf16_f32 v37, v40, v41
	s_nop 0
	v_lshlrev_b32_e32 v38, 16, v37
	v_sub_f32_e32 v38, v40, v38
	v_and_b32_e32 v39, 0xffff0000, v37
	v_sub_f32_e32 v39, v41, v39
	v_cvt_pk_bf16_f32 v38, v38, v39
	global_store_dwordx4 v[88:89], v[34:37], off offset:256
	s_and_saveexec_b64 s[14:15], s[2:3]
	s_cbranch_execz .LBB0_1156
	v_or_b32_e32 v34, 16, v104
	v_ashrrev_i32_e32 v35, 31, v34
	s_waitcnt lgkmcnt(0)
	v_add_f32_e32 v36, v32, v33
	v_lshlrev_b64 v[32:33], 6, v[34:35]
	v_lshl_add_u64 v[32:33], s[40:41], 0, v[32:33]
	v_lshl_add_u64 v[32:33], s[12:13], 2, v[32:33]
	s_lshl_b32 s90, s35, 2
	v_lshl_add_u64 v[32:33], v[32:33], 0, s[90:91]
	global_store_dword v[32:33], v36, off
.LBB0_1156:
	s_or_b64 exec, exec, s[14:15]
	s_waitcnt vmcnt(7)
	v_lshlrev_b32_e32 v32, 16, v68
	s_waitcnt lgkmcnt(0)
	v_and_b32_e32 v33, 0xffff0000, v68
	v_add_f32_e32 v32, 0, v32
	v_add_f32_e32 v33, 0, v33
	v_add_f32_e32 v28, v28, v32
	v_add_f32_e32 v29, v29, v33
	v_lshlrev_b32_e32 v32, 16, v69
	v_and_b32_e32 v33, 0xffff0000, v69
	v_add_f32_e32 v32, 0, v32
	v_add_f32_e32 v33, 0, v33
	v_add_f32_e32 v30, v30, v32
	v_add_f32_e32 v31, v31, v33
	v_lshlrev_b32_e32 v32, 16, v70
	v_and_b32_e32 v33, 0xffff0000, v70
	v_add_f32_e32 v32, 0, v32
	v_add_f32_e32 v33, 0, v33
	v_add_f32_e32 v32, v24, v32
	v_add_f32_e32 v33, v25, v33
	v_lshlrev_b32_e32 v24, 16, v71
	v_and_b32_e32 v25, 0xffff0000, v71
	v_add_f32_e32 v24, 0, v24
	v_add_f32_e32 v25, 0, v25
	v_add_f32_e32 v34, v26, v24
	v_add_f32_e32 v35, v27, v25
	v_cvt_pk_bf16_f32 v24, v28, v29
	s_nop 0
	v_mul_f32_e32 v26, v29, v29
	v_cvt_pk_bf16_f32 v25, v30, v31
	v_fmac_f32_e32 v26, v28, v28
	s_nop 0
	v_mul_f32_e32 v27, v31, v31
	v_fmac_f32_e32 v27, v30, v30
	v_add_f32_e32 v27, v26, v27
	v_cvt_pk_bf16_f32 v26, v32, v33
	s_nop 0
	s_nop 0
	v_mul_f32_e32 v28, v33, v33
	v_fmac_f32_e32 v28, v32, v32
	v_add_f32_e32 v28, v28, v27
	v_cvt_pk_bf16_f32 v27, v34, v35
	s_nop 0
	v_and_b32_e32 v30, 0xffff0000, v27
	v_sub_f32_e32 v30, v35, v30
	global_store_dwordx4 v[74:75], v[24:27], off
	v_mul_f32_e32 v29, v35, v35
	v_fmac_f32_e32 v29, v34, v34
	s_waitcnt vmcnt(7)
	v_lshlrev_b32_e32 v24, 16, v64
	v_and_b32_e32 v25, 0xffff0000, v64
	v_add_f32_e32 v24, 0, v24
	v_add_f32_e32 v25, 0, v25
	v_add_f32_e32 v20, v20, v24
	v_add_f32_e32 v21, v21, v25
	v_lshlrev_b32_e32 v24, 16, v65
	v_and_b32_e32 v25, 0xffff0000, v65
	v_add_f32_e32 v24, 0, v24
	v_add_f32_e32 v25, 0, v25
	v_add_f32_e32 v22, v22, v24
	v_add_f32_e32 v23, v23, v25
	v_lshlrev_b32_e32 v24, 16, v66
	v_and_b32_e32 v25, 0xffff0000, v66
	v_add_f32_e32 v24, 0, v24
	v_add_f32_e32 v25, 0, v25
	v_add_f32_e32 v16, v16, v24
	v_add_f32_e32 v17, v17, v25
	v_lshlrev_b32_e32 v24, 16, v67
	v_and_b32_e32 v25, 0xffff0000, v67
	v_add_f32_e32 v24, 0, v24
	v_add_f32_e32 v25, 0, v25
	v_add_f32_e32 v24, v18, v24
	v_add_f32_e32 v25, v19, v25
	v_cvt_pk_bf16_f32 v18, v20, v21
	v_add_f32_e32 v28, v29, v28
	s_nop 0
	v_mul_f32_e32 v19, v21, v21
	v_fmac_f32_e32 v19, v20, v20
	v_add_f32_e32 v20, v19, v28
	v_cvt_pk_bf16_f32 v19, v22, v23
	s_nop 0
	v_and_b32_e32 v26, 0xffff0000, v19
	v_sub_f32_e32 v26, v23, v26
	s_nop 0
	v_mul_f32_e32 v21, v23, v23
	v_fmac_f32_e32 v21, v22, v22
	v_add_f32_e32 v21, v21, v20
	v_cvt_pk_bf16_f32 v20, v16, v17
	s_nop 0
	v_mul_f32_e32 v17, v17, v17
	v_fmac_f32_e32 v17, v16, v16
	v_add_f32_e32 v16, v17, v21
	v_mul_f32_e32 v17, v25, v25
	v_fmac_f32_e32 v17, v24, v24
	v_add_f32_e32 v16, v17, v16
	ds_bpermute_b32 v17, v136, v16
	s_waitcnt lgkmcnt(0)
	v_add_f32_e32 v16, v16, v17
	ds_bpermute_b32 v17, v137, v16
	v_cvt_pk_bf16_f32 v21, v24, v25
	s_nop 0
	v_lshlrev_b32_e32 v22, 16, v21
	v_sub_f32_e32 v22, v24, v22
	v_and_b32_e32 v23, 0xffff0000, v21
	v_sub_f32_e32 v23, v25, v23
	v_cvt_pk_bf16_f32 v22, v22, v23
	global_store_dwordx4 v[74:75], v[18:21], off offset:256
	s_and_saveexec_b64 s[14:15], s[2:3]
	s_cbranch_execz .LBB0_1158
	s_waitcnt lgkmcnt(0)
	v_add_f32_e32 v18, v16, v17
	v_lshlrev_b64 v[16:17], 6, v[72:73]
	v_lshl_add_u64 v[16:17], s[40:41], 0, v[16:17]
	v_lshl_add_u64 v[16:17], s[12:13], 2, v[16:17]
	s_lshl_b32 s90, s35, 2
	v_lshl_add_u64 v[16:17], v[16:17], 0, s[90:91]
	global_store_dword v[16:17], v18, off
.LBB0_1158:
	s_or_b64 exec, exec, s[14:15]
	s_waitcnt vmcnt(5)
	v_lshlrev_b32_e32 v16, 16, v52
	s_waitcnt lgkmcnt(0)
	v_and_b32_e32 v17, 0xffff0000, v52
	v_add_f32_e32 v16, 0, v16
	v_add_f32_e32 v17, 0, v17
	v_add_f32_e32 v12, v12, v16
	v_add_f32_e32 v13, v13, v17
	v_lshlrev_b32_e32 v16, 16, v53
	v_and_b32_e32 v17, 0xffff0000, v53
	v_add_f32_e32 v16, 0, v16
	v_add_f32_e32 v17, 0, v17
	v_add_f32_e32 v14, v14, v16
	v_add_f32_e32 v15, v15, v17
	v_lshlrev_b32_e32 v16, 16, v54
	v_and_b32_e32 v17, 0xffff0000, v54
	v_add_f32_e32 v16, 0, v16
	v_add_f32_e32 v17, 0, v17
	v_add_f32_e32 v16, v8, v16
	v_add_f32_e32 v17, v9, v17
	v_lshlrev_b32_e32 v8, 16, v55
	v_and_b32_e32 v9, 0xffff0000, v55
	v_add_f32_e32 v8, 0, v8
	v_add_f32_e32 v9, 0, v9
	v_add_f32_e32 v18, v10, v8
	v_add_f32_e32 v19, v11, v9
	v_cvt_pk_bf16_f32 v8, v12, v13
	s_nop 0
	v_mul_f32_e32 v10, v13, v13
	v_cvt_pk_bf16_f32 v9, v14, v15
	v_fmac_f32_e32 v10, v12, v12
	s_nop 0
	v_mul_f32_e32 v11, v15, v15
	v_fmac_f32_e32 v11, v14, v14
	v_add_f32_e32 v11, v10, v11
	v_cvt_pk_bf16_f32 v10, v16, v17
	s_nop 0
	s_nop 0
	v_mul_f32_e32 v12, v17, v17
	v_fmac_f32_e32 v12, v16, v16
	v_add_f32_e32 v12, v12, v11
	v_cvt_pk_bf16_f32 v11, v18, v19
	s_nop 0
	v_and_b32_e32 v14, 0xffff0000, v11
	v_sub_f32_e32 v14, v19, v14
	global_store_dwordx4 v[58:59], v[8:11], off
	v_mul_f32_e32 v13, v19, v19
	v_fmac_f32_e32 v13, v18, v18
	s_waitcnt vmcnt(5)
	v_lshlrev_b32_e32 v8, 16, v48
	v_and_b32_e32 v9, 0xffff0000, v48
	v_add_f32_e32 v8, 0, v8
	v_add_f32_e32 v9, 0, v9
	v_add_f32_e32 v4, v4, v8
	v_add_f32_e32 v5, v5, v9
	v_lshlrev_b32_e32 v8, 16, v49
	v_and_b32_e32 v9, 0xffff0000, v49
	v_add_f32_e32 v8, 0, v8
	v_add_f32_e32 v9, 0, v9
	v_add_f32_e32 v6, v6, v8
	v_add_f32_e32 v7, v7, v9
	v_lshlrev_b32_e32 v8, 16, v50
	v_and_b32_e32 v9, 0xffff0000, v50
	v_add_f32_e32 v8, 0, v8
	v_add_f32_e32 v9, 0, v9
	v_add_f32_e32 v0, v0, v8
	v_add_f32_e32 v1, v1, v9
	v_lshlrev_b32_e32 v8, 16, v51
	v_and_b32_e32 v9, 0xffff0000, v51
	v_add_f32_e32 v8, 0, v8
	v_add_f32_e32 v9, 0, v9
	v_add_f32_e32 v8, v2, v8
	v_add_f32_e32 v9, v3, v9
	v_cvt_pk_bf16_f32 v2, v4, v5
	v_add_f32_e32 v12, v13, v12
	s_nop 0
	v_mul_f32_e32 v3, v5, v5
	v_fmac_f32_e32 v3, v4, v4
	v_add_f32_e32 v4, v3, v12
	v_cvt_pk_bf16_f32 v3, v6, v7
	s_nop 0
	v_and_b32_e32 v10, 0xffff0000, v3
	v_sub_f32_e32 v10, v7, v10
	s_nop 0
	v_mul_f32_e32 v5, v7, v7
	v_fmac_f32_e32 v5, v6, v6
	v_add_f32_e32 v5, v5, v4
	v_cvt_pk_bf16_f32 v4, v0, v1
	s_nop 0
	v_mul_f32_e32 v1, v1, v1
	v_fmac_f32_e32 v1, v0, v0
	v_add_f32_e32 v0, v1, v5
	v_mul_f32_e32 v1, v9, v9
	v_fmac_f32_e32 v1, v8, v8
	v_add_f32_e32 v0, v1, v0
	ds_bpermute_b32 v1, v136, v0
	s_waitcnt lgkmcnt(0)
	v_add_f32_e32 v0, v0, v1
	ds_bpermute_b32 v1, v137, v0
	v_cvt_pk_bf16_f32 v5, v8, v9
	s_nop 0
	v_lshlrev_b32_e32 v6, 16, v5
	v_sub_f32_e32 v6, v8, v6
	v_and_b32_e32 v7, 0xffff0000, v5
	v_sub_f32_e32 v7, v9, v7
	v_cvt_pk_bf16_f32 v6, v6, v7
	global_store_dwordx4 v[58:59], v[2:5], off offset:256
	s_and_saveexec_b64 s[14:15], s[2:3]
	s_cbranch_execz .LBB0_1160
	s_waitcnt lgkmcnt(0)
	v_add_f32_e32 v2, v0, v1
	v_lshlrev_b64 v[0:1], 6, v[56:57]
	v_lshl_add_u64 v[0:1], s[40:41], 0, v[0:1]
	v_lshl_add_u64 v[0:1], s[12:13], 2, v[0:1]
	s_lshl_b32 s90, s35, 2
	v_lshl_add_u64 v[0:1], v[0:1], 0, s[90:91]
	global_store_dword v[0:1], v2, off
